# scan v3: per-row v stored transposed in LDS (one 16-byte read per 4 steps); prep step B batched; XA fragments pooled
# baseline (speedup 1.0000x reference)
; #define LAS __attribute__((address_space(3)))
; __device__ __forceinline__ void scan_load_chunk(LAS unsigned char* slot, const float* Wd, const float* V, const bf16_t* RKKB, int p, int rg, int s0, int lt) {
;     ...
;     if (lt < 128) { const int st = lt >> 2, hf = lt & 3; r[6] = *(const u32x4*)(V + (base + st) * 64 + rg * 16 + hf * 4); }
; #pragma unroll
;     for (int j = 0; j < 2; ++j) { const int idx = lt + 256 * j, st = idx >> 4, part = idx & 15; *(LAS u32x4*)(slot + st * SCAN_STEP_B + part * 16) = r[j]; }
; #pragma unroll
;     for (int j = 2; j < 6; ++j) { const int k = lt + 256 * (j - 2), st = k >> 5, rem = k & 31, q = rem >> 3, part = rem & 7; const u32x4 w = r[j];
;         const int Q = (q == 0) ? 4 : (q == 1) ? 2 : (q == 2) ? 3 : 1;
;         LAS f32x4* d = (LAS f32x4*)(slot + st * SCAN_STEP_B + Q * 256 + part * 32);
;         d[0] = (f32x4){bflo(w.x), bfhi(w.x), bflo(w.y), bfhi(w.y)}; d[1] = (f32x4){bflo(w.z), bfhi(w.z), bflo(w.w), bfhi(w.w)}; }
;     if (lt < 128) { const int st = lt >> 2, hf = lt & 3; *(LAS u32x4*)(slot + st * SCAN_STEP_B + 1280 + hf * 16) = r[6]; }
; }
; __device__ __forceinline__ void rwkv_scan_unit(LAS unsigned char* lds, const float* Wd, const float* V, const bf16_t* RKKB, float* Yraw, int p, int rg, int tid) {
;     const int lane = tid & 63, wave = __builtin_amdgcn_readfirstlane(tid >> 6);
;     constexpr int NCH = SEQ / SCAN_CH;
;     scan_load_chunk(lds + (tid >> 8) * SCAN_SLOT_B, Wd, V, RKKB, p, rg, (tid >> 8) * SCAN_CH, tid & 255);
;     __syncthreads();
;     f32x4 S = (f32x4){0.f, 0.f, 0.f, 0.f};
;     const int kq = lane & 15, rl = wave * 4 + (lane >> 4);
;     for (int c = 0; c < NCH; ++c) {
;         if (wave >= 4) { if (c + 2 < NCH) scan_load_chunk(lds + ((c + 2) % 3) * SCAN_SLOT_B, Wd, V, RKKB, p, rg, (c + 2) * SCAN_CH, tid - 256); }
;         else {
;             LAS const unsigned char* sl = lds + (c % 3) * SCAN_SLOT_B + kq * 16;
;             LAS const unsigned char* vl = lds + (c % 3) * SCAN_SLOT_B + 1280 + rl * 4;
;             float* yo = Yraw + ((size_t)p * SEQ + c * SCAN_CH + kq) * 64 + rg * 16 + rl;
;             f32x4 w = *(LAS const f32x4*)(sl), b = *(LAS const f32x4*)(sl + 256), k = *(LAS const f32x4*)(sl + 512), kk = *(LAS const f32x4*)(sl + 768), r = *(LAS const f32x4*)(sl + 1024);
;             float v = *(LAS const float*)(vl); float yp[16];
.LBB0_340:
	s_or_b64 exec, exec, s[6:7]
	v_add3_u32 v14, v14, v10, v22
	s_waitcnt vmcnt(0)
	v_lshlrev_b32_e32 v10, 16, v2
	v_and_b32_e32 v11, 0xffff0000, v2
	v_lshlrev_b32_e32 v12, 16, v3
	v_and_b32_e32 v13, 0xffff0000, v3
	v_lshlrev_b32_e32 v2, 16, v4
	v_and_b32_e32 v3, 0xffff0000, v4
	v_lshlrev_b32_e32 v4, 16, v5
	v_and_b32_e32 v5, 0xffff0000, v5
	ds_write_b128 v14, v[10:13] offset:10752
	ds_write_b128 v14, v[2:5] offset:10768
	s_and_saveexec_b64 s[6:7], s[4:5]
	v_lshrrev_b32_e32 v2, 8, v232
	v_lshlrev_b32_e32 v2, 11, v2
	v_and_b32_e32 v3, 3, v232
	v_lshl_or_b32 v2, v3, 9, v2
	v_and_b32_e32 v3, 0xfc, v232
	v_or_b32_e32 v2, v2, v3
	v_add_u32_e32 v2, 0x1f800, v2
	ds_write_b32 v2, v6
	ds_write_b32 v2, v7 offset:128
	ds_write_b32 v2, v8 offset:256
	ds_write_b32 v2, v9 offset:384
	s_or_b64 exec, exec, s[6:7]
	v_and_b32_e32 v3, 4, v32
	v_cmp_eq_u32_e64 s[6:7], 0, v3
	v_and_b32_e32 v3, 1, v32
	s_ashr_i32 s4, s10, 6
	v_and_b32_e32 v4, 2, v32
	v_cmp_eq_u32_e64 s[10:11], 0, v3
	v_add_u32_e32 v3, 0xffffff00, v32
	v_add_u32_e32 v12, 0x100, v32
	v_add_u32_e32 v14, 0x200, v32
	s_cmp_lt_i32 s4, 4
	v_cmp_eq_u32_e64 s[8:9], 0, v4
	v_ashrrev_i32_e32 v4, 4, v3
	v_ashrrev_i32_e32 v6, 4, v32
	v_ashrrev_i32_e32 v8, 5, v3
	v_ashrrev_i32_e32 v10, 5, v32
	v_ashrrev_i32_e32 v12, 5, v12
	v_ashrrev_i32_e32 v14, 5, v14
	v_ashrrev_i32_e32 v16, 2, v3
	s_movk_i32 s19, 0x540
	s_cselect_b64 s[16:17], -1, 0
	v_mul_lo_u32 v74, v4, s19
	v_mul_lo_u32 v75, v6, s19
	v_mul_lo_u32 v77, v8, s19
	v_mul_lo_u32 v78, v10, s19
	v_mul_lo_u32 v79, v12, s19
	v_mul_lo_u32 v80, v14, s19
	v_mul_lo_u32 v81, v16, s19
	s_and_b32 s23, s20, 7
	s_ashr_i32 s19, s18, 31
	s_lshl_b32 s21, s23, 22
	s_lshl_b64 s[24:25], s[18:19], 20
	v_ashrrev_i32_e32 v17, 31, v16
	v_lshlrev_b32_e32 v19, 5, v32
	s_add_u32 s24, s21, s24
	v_and_b32_e32 v76, 0xe0, v19
	s_addc_u32 s25, 0, s25
	v_lshlrev_b64 v[16:17], 8, v[16:17]
	s_lshl_b32 s20, s20, 3
	v_and_b32_e32 v19, 3, v3
	v_lshl_add_u64 v[16:17], s[24:25], 0, v[16:17]
	s_and_b32 s26, s20, 0xc0
	v_lshlrev_b32_e32 v19, 4, v19
	v_readlane_b32 s20, v254, 47
	v_or3_b32 v16, v16, s26, v19
	v_readlane_b32 s21, v254, 48
	s_lshl_b32 s27, s23, 23
	v_ashrrev_i32_e32 v5, 31, v4
	v_lshl_add_u64 v[46:47], s[20:21], 0, v[16:17]
	s_lshl_b64 s[20:21], s[18:19], 21
	v_ashrrev_i32_e32 v7, 31, v6
	v_ashrrev_i32_e32 v9, 31, v8
	v_ashrrev_i32_e32 v11, 31, v10
	v_ashrrev_i32_e32 v13, 31, v12
	v_ashrrev_i32_e32 v15, 31, v14
	s_add_u32 s20, s27, s20
	v_lshlrev_b32_e32 v18, 4, v3
	s_addc_u32 s21, 0, s21
	v_lshlrev_b64 v[14:15], 9, v[14:15]
	v_lshlrev_b64 v[12:13], 9, v[12:13]
	v_lshlrev_b64 v[10:11], 9, v[10:11]
	v_lshlrev_b64 v[8:9], 9, v[8:9]
	v_lshlrev_b64 v[6:7], 8, v[6:7]
	v_lshlrev_b64 v[4:5], 8, v[4:5]
	v_and_b32_e32 v73, 0xf0, v18
	v_lshl_add_u64 v[14:15], s[20:21], 0, v[14:15]
	v_lshl_add_u64 v[12:13], s[20:21], 0, v[12:13]
	v_lshl_add_u64 v[10:11], s[20:21], 0, v[10:11]
	v_lshl_add_u64 v[8:9], s[20:21], 0, v[8:9]
	v_lshl_add_u64 v[6:7], s[24:25], 0, v[6:7]
	v_readlane_b32 s20, v254, 51
	v_lshl_add_u64 v[4:5], s[24:25], 0, v[4:5]
	v_or_b32_e32 v6, v6, v73
	v_readlane_b32 s21, v254, 52
	v_or_b32_e32 v4, v4, v73
	s_lshl_b64 s[18:19], s[18:19], 12
	v_lshl_add_u64 v[56:57], s[20:21], 0, v[6:7]
	v_lshl_add_u64 v[58:59], s[20:21], 0, v[4:5]
	s_lshl_b32 s20, s23, 14
	s_add_u32 s18, s20, s18
	v_and_b32_e32 v0, 15, v32
	s_addc_u32 s19, 0, s19
	v_bfe_u32 v2, v32, 4, 2
	v_and_b32_e32 v3, 7, v3
	v_or_b32_e32 v4, s18, v0
	v_mov_b32_e32 v5, s19
	v_lshl_or_b32 v2, s4, 2, v2
	v_and_b32_e32 v16, 0x180, v18
	v_lshlrev_b32_e32 v3, 4, v3
	v_lshlrev_b64 v[4:5], 8, v[4:5]
	v_or3_b32 v14, v14, v16, v3
	v_or3_b32 v12, v12, v16, v3
	v_or3_b32 v10, v10, v16, v3
	v_or3_b32 v8, v8, v16, v3
	v_or_b32_e32 v4, s26, v4
	v_ashrrev_i32_e32 v3, 31, v2
	v_lshlrev_b32_e32 v72, 2, v2
	v_lshl_add_u64 v[2:3], v[2:3], 2, v[4:5]
	v_readlane_b32 s28, v254, 49
	v_lshl_add_u64 v[60:61], s[92:93], 0, v[2:3]
	v_mov_b32_e32 v2, v1
	v_mov_b32_e32 v3, v1
	v_lshlrev_b32_e32 v71, 4, v0
	v_cmp_gt_u32_e64 s[4:5], 8, v0
	s_movk_i32 s12, 0x180
	v_readlane_b32 s29, v254, 50
	v_mov_b32_e32 v0, v1
	v_mov_b64_e32 v[4:5], v[2:3]
	s_mov_b32 s22, 0
	v_cmp_gt_i32_e64 s[12:13], s12, v32
	v_and_b32_e32 v82, 48, v18
	v_lshl_add_u64 v[48:49], s[28:29], 0, v[14:15]
	v_lshl_add_u64 v[50:51], s[28:29], 0, v[12:13]
	v_lshl_add_u64 v[52:53], s[28:29], 0, v[10:11]
	v_lshl_add_u64 v[54:55], s[28:29], 0, v[8:9]
	v_mov_b64_e32 v[2:3], v[0:1]
	s_waitcnt lgkmcnt(0)
	s_barrier
	s_and_b64 vcc, exec, s[16:17]
	s_cbranch_vccz .Lscan_noprime
	v_lshlrev_b32_e32 v96, 5, v72
	v_add_u32_e32 v96, 0x1f800, v96
	ds_read_b128 v[116:119], v96
	ds_read_b128 v[132:135], v71 offset:768
	ds_read_b128 v[120:123], v71
	ds_read_b128 v[128:131], v71 offset:512
	ds_read_b128 v[124:127], v71 offset:256
	ds_read_b128 v[136:139], v71 offset:1024
	ds_read_b128 v[156:159], v71 offset:2112
	ds_read_b128 v[144:147], v71 offset:1344
	ds_read_b128 v[152:155], v71 offset:1856
	ds_read_b128 v[148:151], v71 offset:1600
	ds_read_b128 v[160:163], v71 offset:2368

; #define LAS __attribute__((address_space(3)))
; __device__ __forceinline__ float row16_sum(float v) { v += dpp_f<0xB1>(v); v += dpp_f<0x4E>(v); v += dpp_f<0x141>(v); v += dpp_f<0x140>(v); return v; }
; __device__ __forceinline__ void rwkv_scan_unit(LAS unsigned char* lds, const float* Wd, const float* V, const bf16_t* RKKB, float* Yraw, int p, int rg, int tid) {
;     ...
;     for (int c = 0; c < NCH; ++c) {
;         if (wave >= 4) { if (c + 2 < NCH) scan_load_chunk(lds + ((c + 2) % 3) * SCAN_SLOT_B, Wd, V, RKKB, p, rg, (c + 2) * SCAN_CH, tid - 256); }
;         else {
;             LAS const unsigned char* sl = lds + (c % 3) * SCAN_SLOT_B + kq * 16;
;             LAS const unsigned char* vl = lds + (c % 3) * SCAN_SLOT_B + 1280 + rl * 4;
;             float* yo = Yraw + ((size_t)p * SEQ + c * SCAN_CH + kq) * 64 + rg * 16 + rl;
;             f32x4 w = *(LAS const f32x4*)(sl), b = *(LAS const f32x4*)(sl + 256), k = *(LAS const f32x4*)(sl + 512), kk = *(LAS const f32x4*)(sl + 768), r = *(LAS const f32x4*)(sl + 1024);
;             float v = *(LAS const float*)(vl); float yp[16];
; #pragma unroll
;             for (int st = 0; st < SCAN_CH; ++st) {
;                 f32x4 wn = w, bn = b, kn = k, kkn = kk, rn = r; float vn = v;
;                 if (st + 1 < SCAN_CH) { const int o = (st + 1) * SCAN_STEP_B;
;                     wn = *(LAS const f32x4*)(sl + o); bn = *(LAS const f32x4*)(sl + o + 256); kn = *(LAS const f32x4*)(sl + o + 512); kkn = *(LAS const f32x4*)(sl + o + 768); rn = *(LAS const f32x4*)(sl + o + 1024);
;                     vn = *(LAS const float*)(vl + o); }
;                 float sa = (S[0] * kk[0] + S[1] * kk[1]) + (S[2] * kk[2] + S[3] * kk[3]);
;                 const f32x4 kvt = k * v;
;                 sa = -row16_sum(sa);
;                 S = S * w + (b * sa + kvt);
;                 yp[st & 15] = (S[0] * r[0] + S[1] * r[1]) + (S[2] * r[2] + S[3] * r[3]);
;                 if ((st & 15) == 15) yo[(size_t)(st - 15) * 64] = tr16_sum(yp, kq);
;                 w = wn; b = bn; k = kn; kk = kkn; r = rn; v = vn;
.Lscan_top:
	s_mul_i32 s18, s22, 0xab
	s_bfe_u32 s18, s18, 0x70009
	s_mul_i32 s18, s18, 3
	s_sub_i32 s18, s22, s18
	s_and_b32 s18, s18, 0xff
	s_mul_i32 s18, s18, 0xa800
	s_add_i32 s19, s18, 0xa800
	s_cmp_eq_u32 s19, 0x1f800
	s_cselect_b32 s19, 0, s19
	v_add_u32_e32 v84, s18, v71
	v_add_u32_e32 v83, s18, v72
	v_add_u32_e32 v86, s19, v71
	v_add_u32_e32 v85, s19, v72
	v_lshl_add_u64 v[62:63], v[60:61], 0, s[14:15]
	s_mov_b64 s[20:21], 0x16100000
	v_lshl_add_u64 v[88:89], v[62:63], 0, s[20:21]
	s_mov_b64 s[20:21], 0x16101000
	v_lshl_add_u64 v[90:91], v[62:63], 0, s[20:21]
	s_lshr_b32 s20, s18, 15
	s_lshl_b32 s20, s20, 11
	s_add_i32 s20, s20, 0x1f800
	v_lshl_add_u32 v96, v72, 5, s20
	s_lshr_b32 s21, s19, 15
	s_lshl_b32 s21, s21, 11
	s_add_i32 s21, s21, 0x1f800
	v_lshl_add_u32 v97, v72, 5, s21
	s_waitcnt lgkmcnt(5)
	v_pk_mul_f32 v[10:11], v[2:3], v[132:133]
	v_pk_fma_f32 v[10:11], v[4:5], v[134:135], v[10:11]
	v_pk_mul_f32 v[6:7], v[128:129], v[116:117] op_sel_hi:[1,0]
	v_add_f32_e32 v12, v10, v11
	v_pk_mul_f32 v[8:9], v[130:131], v[116:117] op_sel_hi:[1,0]
	v_pk_fma_f32 v[6:7], v[2:3], v[120:121], v[6:7]
	v_add_f32_dpp v12, v12, v12 quad_perm:[1,0,3,2] row_mask:0xf bank_mask:0xf bound_ctrl:1
	v_pk_fma_f32 v[8:9], v[4:5], v[122:123], v[8:9]
	ds_read_b128 v[180:183], v84 offset:3456
	v_add_f32_dpp v12, v12, v12 quad_perm:[2,3,0,1] row_mask:0xf bank_mask:0xf bound_ctrl:1
	ds_read_b128 v[168:171], v84 offset:2688
	ds_read_b128 v[176:179], v84 offset:3200
	v_add_f32_dpp v12, v12, v12 row_half_mirror row_mask:0xf bank_mask:0xf bound_ctrl:1
	ds_read_b128 v[172:175], v84 offset:2944
	ds_read_b128 v[184:187], v84 offset:3712
	v_add_f32_dpp v12, v12, v12 row_mirror row_mask:0xf bank_mask:0xf bound_ctrl:1
	v_pk_fma_f32 v[2:3], v[124:125], v[12:13], v[6:7] op_sel_hi:[1,0,1] neg_lo:[0,1,0] neg_hi:[0,1,0]
	v_pk_fma_f32 v[4:5], v[126:127], v[12:13], v[8:9] op_sel_hi:[1,0,1] neg_lo:[0,1,0] neg_hi:[0,1,0]
	s_waitcnt lgkmcnt(5)
	v_pk_mul_f32 v[10:11], v[2:3], v[156:157]
	v_pk_fma_f32 v[10:11], v[4:5], v[158:159], v[10:11]
	v_pk_mul_f32 v[14:15], v[2:3], v[136:137]
	v_add_f32_e32 v12, v10, v11
	v_pk_fma_f32 v[14:15], v[4:5], v[138:139], v[14:15]
	v_add_f32_e32 v100, v14, v15
	v_add_f32_dpp v12, v12, v12 quad_perm:[1,0,3,2] row_mask:0xf bank_mask:0xf bound_ctrl:1
	v_pk_mul_f32 v[6:7], v[152:153], v[116:117] op_sel:[0,1] op_sel_hi:[1,1]
	v_pk_mul_f32 v[8:9], v[154:155], v[116:117] op_sel:[0,1] op_sel_hi:[1,1]
	v_add_f32_dpp v12, v12, v12 quad_perm:[2,3,0,1] row_mask:0xf bank_mask:0xf bound_ctrl:1
	v_pk_fma_f32 v[6:7], v[2:3], v[144:145], v[6:7]
	v_pk_fma_f32 v[8:9], v[4:5], v[146:147], v[8:9]
	v_add_f32_dpp v12, v12, v12 row_half_mirror row_mask:0xf bank_mask:0xf bound_ctrl:1
	ds_read_b128 v[34:37], v84 offset:4800
	ds_read_b128 v[22:25], v84 offset:4032
	v_add_f32_dpp v12, v12, v12 row_mirror row_mask:0xf bank_mask:0xf bound_ctrl:1
	ds_read_b128 v[30:33], v84 offset:4544
	ds_read_b128 v[26:29], v84 offset:4288
	ds_read_b128 v[38:41], v84 offset:5056
	v_pk_fma_f32 v[2:3], v[148:149], v[12:13], v[6:7] op_sel_hi:[1,0,1] neg_lo:[0,1,0] neg_hi:[0,1,0]
	v_pk_fma_f32 v[4:5], v[150:151], v[12:13], v[8:9] op_sel_hi:[1,0,1] neg_lo:[0,1,0] neg_hi:[0,1,0]
	s_waitcnt lgkmcnt(5)
	v_pk_mul_f32 v[10:11], v[2:3], v[180:181]
	v_pk_fma_f32 v[10:11], v[4:5], v[182:183], v[10:11]
	v_pk_mul_f32 v[14:15], v[2:3], v[160:161]
	v_add_f32_e32 v12, v10, v11
	v_pk_fma_f32 v[14:15], v[4:5], v[162:163], v[14:15]
	v_add_f32_e32 v101, v14, v15
	v_add_f32_dpp v12, v12, v12 quad_perm:[1,0,3,2] row_mask:0xf bank_mask:0xf bound_ctrl:1
	v_pk_mul_f32 v[6:7], v[176:177], v[118:119] op_sel_hi:[1,0]
	v_pk_mul_f32 v[8:9], v[178:179], v[118:119] op_sel_hi:[1,0]
	v_add_f32_dpp v12, v12, v12 quad_perm:[2,3,0,1] row_mask:0xf bank_mask:0xf bound_ctrl:1
	v_pk_fma_f32 v[6:7], v[2:3], v[168:169], v[6:7]
	v_pk_fma_f32 v[8:9], v[4:5], v[170:171], v[8:9]
	v_add_f32_dpp v12, v12, v12 row_half_mirror row_mask:0xf bank_mask:0xf bound_ctrl:1
	ds_read_b128 v[132:135], v84 offset:6144
	ds_read_b128 v[120:123], v84 offset:5376
	v_add_f32_dpp v12, v12, v12 row_mirror row_mask:0xf bank_mask:0xf bound_ctrl:1
	ds_read_b128 v[128:131], v84 offset:5888
	ds_read_b128 v[92:95], v96 offset:16
	ds_read_b128 v[124:127], v84 offset:5632
	ds_read_b128 v[136:139], v84 offset:6400
	v_pk_fma_f32 v[2:3], v[172:173], v[12:13], v[6:7] op_sel_hi:[1,0,1] neg_lo:[0,1,0] neg_hi:[0,1,0]
	v_pk_fma_f32 v[4:5], v[174:175], v[12:13], v[8:9] op_sel_hi:[1,0,1] neg_lo:[0,1,0] neg_hi:[0,1,0]
	s_waitcnt lgkmcnt(6)
	v_pk_mul_f32 v[10:11], v[2:3], v[34:35]
	v_pk_fma_f32 v[10:11], v[4:5], v[36:37], v[10:11]
	v_pk_mul_f32 v[14:15], v[2:3], v[184:185]
	v_add_f32_e32 v12, v10, v11
	v_pk_fma_f32 v[14:15], v[4:5], v[186:187], v[14:15]
	v_add_f32_e32 v102, v14, v15
	v_add_f32_dpp v12, v12, v12 quad_perm:[1,0,3,2] row_mask:0xf bank_mask:0xf bound_ctrl:1
	v_pk_mul_f32 v[6:7], v[30:31], v[118:119] op_sel:[0,1] op_sel_hi:[1,1]
	v_pk_mul_f32 v[8:9], v[32:33], v[118:119] op_sel:[0,1] op_sel_hi:[1,1]
	v_add_f32_dpp v12, v12, v12 quad_perm:[2,3,0,1] row_mask:0xf bank_mask:0xf bound_ctrl:1
	v_pk_fma_f32 v[6:7], v[2:3], v[22:23], v[6:7]
	v_pk_fma_f32 v[8:9], v[4:5], v[24:25], v[8:9]
	v_add_f32_dpp v12, v12, v12 row_half_mirror row_mask:0xf bank_mask:0xf bound_ctrl:1
	ds_read_b128 v[156:159], v84 offset:7488
	ds_read_b128 v[144:147], v84 offset:6720
	v_add_f32_dpp v12, v12, v12 row_mirror row_mask:0xf bank_mask:0xf bound_ctrl:1
	ds_read_b128 v[152:155], v84 offset:7232
	ds_read_b128 v[148:151], v84 offset:6976
	ds_read_b128 v[160:163], v84 offset:7744
	v_pk_fma_f32 v[2:3], v[26:27], v[12:13], v[6:7] op_sel_hi:[1,0,1] neg_lo:[0,1,0] neg_hi:[0,1,0]
	v_pk_fma_f32 v[4:5], v[28:29], v[12:13], v[8:9] op_sel_hi:[1,0,1] neg_lo:[0,1,0] neg_hi:[0,1,0]
	s_waitcnt lgkmcnt(5)
; #define LAS __attribute__((address_space(3)))
; __device__ __forceinline__ float row16_sum(float v) { v += dpp_f<0xB1>(v); v += dpp_f<0x4E>(v); v += dpp_f<0x141>(v); v += dpp_f<0x140>(v); return v; }
; __device__ __forceinline__ void rwkv_scan_unit(LAS unsigned char* lds, const float* Wd, const float* V, const bf16_t* RKKB, float* Yraw, int p, int rg, int tid) {
;     ...
;             for (int st = 0; st < SCAN_CH; ++st) {
;                 f32x4 wn = w, bn = b, kn = k, kkn = kk, rn = r; float vn = v;
;                 if (st + 1 < SCAN_CH) { const int o = (st + 1) * SCAN_STEP_B;
;                     wn = *(LAS const f32x4*)(sl + o); bn = *(LAS const f32x4*)(sl + o + 256); kn = *(LAS const f32x4*)(sl + o + 512); kkn = *(LAS const f32x4*)(sl + o + 768); rn = *(LAS const f32x4*)(sl + o + 1024);
;                     vn = *(LAS const float*)(vl + o); }
;                 float sa = (S[0] * kk[0] + S[1] * kk[1]) + (S[2] * kk[2] + S[3] * kk[3]);
;                 const f32x4 kvt = k * v;
;                 sa = -row16_sum(sa);
;                 S = S * w + (b * sa + kvt);
;                 yp[st & 15] = (S[0] * r[0] + S[1] * r[1]) + (S[2] * r[2] + S[3] * r[3]);
;                 if ((st & 15) == 15) yo[(size_t)(st - 15) * 64] = tr16_sum(yp, kq);
;                 w = wn; b = bn; k = kn; kk = kkn; r = rn; v = vn;
	v_pk_mul_f32 v[10:11], v[2:3], v[132:133]
	v_pk_fma_f32 v[10:11], v[4:5], v[134:135], v[10:11]
	v_pk_mul_f32 v[14:15], v[2:3], v[38:39]
	v_add_f32_e32 v12, v10, v11
	v_pk_fma_f32 v[14:15], v[4:5], v[40:41], v[14:15]
	v_add_f32_e32 v103, v14, v15
	v_add_f32_dpp v12, v12, v12 quad_perm:[1,0,3,2] row_mask:0xf bank_mask:0xf bound_ctrl:1
	v_pk_mul_f32 v[6:7], v[128:129], v[92:93] op_sel_hi:[1,0]
	v_pk_mul_f32 v[8:9], v[130:131], v[92:93] op_sel_hi:[1,0]
	v_add_f32_dpp v12, v12, v12 quad_perm:[2,3,0,1] row_mask:0xf bank_mask:0xf bound_ctrl:1
	v_pk_fma_f32 v[6:7], v[2:3], v[120:121], v[6:7]
	v_pk_fma_f32 v[8:9], v[4:5], v[122:123], v[8:9]
	v_add_f32_dpp v12, v12, v12 row_half_mirror row_mask:0xf bank_mask:0xf bound_ctrl:1
	ds_read_b128 v[180:183], v84 offset:8832
	ds_read_b128 v[168:171], v84 offset:8064
	v_add_f32_dpp v12, v12, v12 row_mirror row_mask:0xf bank_mask:0xf bound_ctrl:1
	ds_read_b128 v[176:179], v84 offset:8576
	ds_read_b128 v[172:175], v84 offset:8320
	ds_read_b128 v[184:187], v84 offset:9088
	v_pk_fma_f32 v[2:3], v[124:125], v[12:13], v[6:7] op_sel_hi:[1,0,1] neg_lo:[0,1,0] neg_hi:[0,1,0]
	v_pk_fma_f32 v[4:5], v[126:127], v[12:13], v[8:9] op_sel_hi:[1,0,1] neg_lo:[0,1,0] neg_hi:[0,1,0]
	s_waitcnt lgkmcnt(5)
	v_pk_mul_f32 v[10:11], v[2:3], v[156:157]
	v_pk_fma_f32 v[10:11], v[4:5], v[158:159], v[10:11]
	v_pk_mul_f32 v[14:15], v[2:3], v[136:137]
	v_add_f32_e32 v12, v10, v11
	v_pk_fma_f32 v[14:15], v[4:5], v[138:139], v[14:15]
	v_add_f32_e32 v104, v14, v15
	v_add_f32_dpp v12, v12, v12 quad_perm:[1,0,3,2] row_mask:0xf bank_mask:0xf bound_ctrl:1
	v_pk_mul_f32 v[6:7], v[152:153], v[92:93] op_sel:[0,1] op_sel_hi:[1,1]
	v_pk_mul_f32 v[8:9], v[154:155], v[92:93] op_sel:[0,1] op_sel_hi:[1,1]
	v_add_f32_dpp v12, v12, v12 quad_perm:[2,3,0,1] row_mask:0xf bank_mask:0xf bound_ctrl:1
	v_pk_fma_f32 v[6:7], v[2:3], v[144:145], v[6:7]
	v_pk_fma_f32 v[8:9], v[4:5], v[146:147], v[8:9]
	v_add_f32_dpp v12, v12, v12 row_half_mirror row_mask:0xf bank_mask:0xf bound_ctrl:1
	ds_read_b128 v[34:37], v84 offset:10176
	ds_read_b128 v[22:25], v84 offset:9408
	v_add_f32_dpp v12, v12, v12 row_mirror row_mask:0xf bank_mask:0xf bound_ctrl:1
	ds_read_b128 v[30:33], v84 offset:9920
	ds_read_b128 v[26:29], v84 offset:9664
	ds_read_b128 v[38:41], v84 offset:10432
	v_pk_fma_f32 v[2:3], v[148:149], v[12:13], v[6:7] op_sel_hi:[1,0,1] neg_lo:[0,1,0] neg_hi:[0,1,0]
	v_pk_fma_f32 v[4:5], v[150:151], v[12:13], v[8:9] op_sel_hi:[1,0,1] neg_lo:[0,1,0] neg_hi:[0,1,0]
	s_waitcnt lgkmcnt(5)
	v_pk_mul_f32 v[10:11], v[2:3], v[180:181]
	v_pk_fma_f32 v[10:11], v[4:5], v[182:183], v[10:11]
	v_pk_mul_f32 v[14:15], v[2:3], v[160:161]
	v_add_f32_e32 v12, v10, v11
	v_pk_fma_f32 v[14:15], v[4:5], v[162:163], v[14:15]
	v_add_f32_e32 v105, v14, v15
	v_add_f32_dpp v12, v12, v12 quad_perm:[1,0,3,2] row_mask:0xf bank_mask:0xf bound_ctrl:1
	v_pk_mul_f32 v[6:7], v[176:177], v[94:95] op_sel_hi:[1,0]
	v_pk_mul_f32 v[8:9], v[178:179], v[94:95] op_sel_hi:[1,0]
	v_add_f32_dpp v12, v12, v12 quad_perm:[2,3,0,1] row_mask:0xf bank_mask:0xf bound_ctrl:1
	v_pk_fma_f32 v[6:7], v[2:3], v[168:169], v[6:7]
	v_pk_fma_f32 v[8:9], v[4:5], v[170:171], v[8:9]
	v_add_f32_dpp v12, v12, v12 row_half_mirror row_mask:0xf bank_mask:0xf bound_ctrl:1
	ds_read_b128 v[132:135], v84 offset:11520
	ds_read_b128 v[120:123], v84 offset:10752
	v_add_f32_dpp v12, v12, v12 row_mirror row_mask:0xf bank_mask:0xf bound_ctrl:1
	ds_read_b128 v[128:131], v84 offset:11264
	ds_read_b128 v[116:119], v96 offset:32
	ds_read_b128 v[124:127], v84 offset:11008
	ds_read_b128 v[136:139], v84 offset:11776
	v_pk_fma_f32 v[2:3], v[172:173], v[12:13], v[6:7] op_sel_hi:[1,0,1] neg_lo:[0,1,0] neg_hi:[0,1,0]
	v_pk_fma_f32 v[4:5], v[174:175], v[12:13], v[8:9] op_sel_hi:[1,0,1] neg_lo:[0,1,0] neg_hi:[0,1,0]
	s_waitcnt lgkmcnt(6)
	v_pk_mul_f32 v[10:11], v[2:3], v[34:35]
	v_pk_fma_f32 v[10:11], v[4:5], v[36:37], v[10:11]
	v_pk_mul_f32 v[14:15], v[2:3], v[184:185]
	v_add_f32_e32 v12, v10, v11
	v_pk_fma_f32 v[14:15], v[4:5], v[186:187], v[14:15]
	v_add_f32_e32 v106, v14, v15
	v_add_f32_dpp v12, v12, v12 quad_perm:[1,0,3,2] row_mask:0xf bank_mask:0xf bound_ctrl:1
	v_pk_mul_f32 v[6:7], v[30:31], v[94:95] op_sel:[0,1] op_sel_hi:[1,1]
	v_pk_mul_f32 v[8:9], v[32:33], v[94:95] op_sel:[0,1] op_sel_hi:[1,1]
	v_add_f32_dpp v12, v12, v12 quad_perm:[2,3,0,1] row_mask:0xf bank_mask:0xf bound_ctrl:1
	v_pk_fma_f32 v[6:7], v[2:3], v[22:23], v[6:7]
	v_pk_fma_f32 v[8:9], v[4:5], v[24:25], v[8:9]
	v_add_f32_dpp v12, v12, v12 row_half_mirror row_mask:0xf bank_mask:0xf bound_ctrl:1
	ds_read_b128 v[156:159], v84 offset:12864
	ds_read_b128 v[144:147], v84 offset:12096
	v_add_f32_dpp v12, v12, v12 row_mirror row_mask:0xf bank_mask:0xf bound_ctrl:1
	ds_read_b128 v[152:155], v84 offset:12608
	ds_read_b128 v[148:151], v84 offset:12352
	ds_read_b128 v[160:163], v84 offset:13120
	v_pk_fma_f32 v[2:3], v[26:27], v[12:13], v[6:7] op_sel_hi:[1,0,1] neg_lo:[0,1,0] neg_hi:[0,1,0]
	v_pk_fma_f32 v[4:5], v[28:29], v[12:13], v[8:9] op_sel_hi:[1,0,1] neg_lo:[0,1,0] neg_hi:[0,1,0]
	s_waitcnt lgkmcnt(5)
; #define LAS __attribute__((address_space(3)))
; __device__ __forceinline__ float row16_sum(float v) { v += dpp_f<0xB1>(v); v += dpp_f<0x4E>(v); v += dpp_f<0x141>(v); v += dpp_f<0x140>(v); return v; }
; __device__ __forceinline__ void rwkv_scan_unit(LAS unsigned char* lds, const float* Wd, const float* V, const bf16_t* RKKB, float* Yraw, int p, int rg, int tid) {
;     ...
;             for (int st = 0; st < SCAN_CH; ++st) {
;                 f32x4 wn = w, bn = b, kn = k, kkn = kk, rn = r; float vn = v;
;                 if (st + 1 < SCAN_CH) { const int o = (st + 1) * SCAN_STEP_B;
;                     wn = *(LAS const f32x4*)(sl + o); bn = *(LAS const f32x4*)(sl + o + 256); kn = *(LAS const f32x4*)(sl + o + 512); kkn = *(LAS const f32x4*)(sl + o + 768); rn = *(LAS const f32x4*)(sl + o + 1024);
;                     vn = *(LAS const float*)(vl + o); }
;                 float sa = (S[0] * kk[0] + S[1] * kk[1]) + (S[2] * kk[2] + S[3] * kk[3]);
;                 const f32x4 kvt = k * v;
;                 sa = -row16_sum(sa);
;                 S = S * w + (b * sa + kvt);
;                 yp[st & 15] = (S[0] * r[0] + S[1] * r[1]) + (S[2] * r[2] + S[3] * r[3]);
;                 if ((st & 15) == 15) yo[(size_t)(st - 15) * 64] = tr16_sum(yp, kq);
;                 w = wn; b = bn; k = kn; kk = kkn; r = rn; v = vn;
	v_pk_mul_f32 v[10:11], v[2:3], v[132:133]
	v_pk_fma_f32 v[10:11], v[4:5], v[134:135], v[10:11]
	v_pk_mul_f32 v[14:15], v[2:3], v[38:39]
	v_add_f32_e32 v12, v10, v11
	v_pk_fma_f32 v[14:15], v[4:5], v[40:41], v[14:15]
	v_add_f32_e32 v107, v14, v15
	v_add_f32_dpp v12, v12, v12 quad_perm:[1,0,3,2] row_mask:0xf bank_mask:0xf bound_ctrl:1
	v_pk_mul_f32 v[6:7], v[128:129], v[116:117] op_sel_hi:[1,0]
	v_pk_mul_f32 v[8:9], v[130:131], v[116:117] op_sel_hi:[1,0]
	v_add_f32_dpp v12, v12, v12 quad_perm:[2,3,0,1] row_mask:0xf bank_mask:0xf bound_ctrl:1
	v_pk_fma_f32 v[6:7], v[2:3], v[120:121], v[6:7]
	v_pk_fma_f32 v[8:9], v[4:5], v[122:123], v[8:9]
	v_add_f32_dpp v12, v12, v12 row_half_mirror row_mask:0xf bank_mask:0xf bound_ctrl:1
	ds_read_b128 v[180:183], v84 offset:14208
	ds_read_b128 v[168:171], v84 offset:13440
	v_add_f32_dpp v12, v12, v12 row_mirror row_mask:0xf bank_mask:0xf bound_ctrl:1
	ds_read_b128 v[176:179], v84 offset:13952
	ds_read_b128 v[172:175], v84 offset:13696
	ds_read_b128 v[184:187], v84 offset:14464
	v_pk_fma_f32 v[2:3], v[124:125], v[12:13], v[6:7] op_sel_hi:[1,0,1] neg_lo:[0,1,0] neg_hi:[0,1,0]
	v_pk_fma_f32 v[4:5], v[126:127], v[12:13], v[8:9] op_sel_hi:[1,0,1] neg_lo:[0,1,0] neg_hi:[0,1,0]
	s_waitcnt lgkmcnt(5)
	v_pk_mul_f32 v[10:11], v[2:3], v[156:157]
	v_pk_fma_f32 v[10:11], v[4:5], v[158:159], v[10:11]
	v_pk_mul_f32 v[14:15], v[2:3], v[136:137]
	v_add_f32_e32 v12, v10, v11
	v_pk_fma_f32 v[14:15], v[4:5], v[138:139], v[14:15]
	v_add_f32_e32 v44, v14, v15
	v_add_f32_dpp v12, v12, v12 quad_perm:[1,0,3,2] row_mask:0xf bank_mask:0xf bound_ctrl:1
	v_add_f32_dpp v100, v100, v100 row_mirror row_mask:0xf bank_mask:0x3 bound_ctrl:1
	v_add_f32_dpp v100, v44, v44 row_mirror row_mask:0xf bank_mask:0xc bound_ctrl:1
	v_add_f32_dpp v12, v12, v12 quad_perm:[2,3,0,1] row_mask:0xf bank_mask:0xf bound_ctrl:1
	v_pk_mul_f32 v[6:7], v[152:153], v[116:117] op_sel:[0,1] op_sel_hi:[1,1]
	v_pk_mul_f32 v[8:9], v[154:155], v[116:117] op_sel:[0,1] op_sel_hi:[1,1]
	v_add_f32_dpp v12, v12, v12 row_half_mirror row_mask:0xf bank_mask:0xf bound_ctrl:1
	v_pk_fma_f32 v[6:7], v[2:3], v[144:145], v[6:7]
	v_pk_fma_f32 v[8:9], v[4:5], v[146:147], v[8:9]
	v_add_f32_dpp v12, v12, v12 row_mirror row_mask:0xf bank_mask:0xf bound_ctrl:1
	ds_read_b128 v[34:37], v84 offset:15552
	ds_read_b128 v[22:25], v84 offset:14784
	ds_read_b128 v[30:33], v84 offset:15296
	ds_read_b128 v[26:29], v84 offset:15040
	ds_read_b128 v[38:41], v84 offset:15808
	v_pk_fma_f32 v[2:3], v[148:149], v[12:13], v[6:7] op_sel_hi:[1,0,1] neg_lo:[0,1,0] neg_hi:[0,1,0]
	v_pk_fma_f32 v[4:5], v[150:151], v[12:13], v[8:9] op_sel_hi:[1,0,1] neg_lo:[0,1,0] neg_hi:[0,1,0]
	s_waitcnt lgkmcnt(5)
	v_pk_mul_f32 v[10:11], v[2:3], v[180:181]
	v_pk_fma_f32 v[10:11], v[4:5], v[182:183], v[10:11]
	v_pk_mul_f32 v[14:15], v[2:3], v[160:161]
	v_add_f32_e32 v12, v10, v11
	v_pk_fma_f32 v[14:15], v[4:5], v[162:163], v[14:15]
	v_add_f32_e32 v44, v14, v15
	v_add_f32_dpp v12, v12, v12 quad_perm:[1,0,3,2] row_mask:0xf bank_mask:0xf bound_ctrl:1
	v_add_f32_dpp v101, v101, v101 row_mirror row_mask:0xf bank_mask:0x3 bound_ctrl:1
	v_add_f32_dpp v101, v44, v44 row_mirror row_mask:0xf bank_mask:0xc bound_ctrl:1
	v_add_f32_dpp v12, v12, v12 quad_perm:[2,3,0,1] row_mask:0xf bank_mask:0xf bound_ctrl:1
	v_pk_mul_f32 v[6:7], v[176:177], v[118:119] op_sel_hi:[1,0]
	v_pk_mul_f32 v[8:9], v[178:179], v[118:119] op_sel_hi:[1,0]
	v_add_f32_dpp v12, v12, v12 row_half_mirror row_mask:0xf bank_mask:0xf bound_ctrl:1
	v_pk_fma_f32 v[6:7], v[2:3], v[168:169], v[6:7]
	v_pk_fma_f32 v[8:9], v[4:5], v[170:171], v[8:9]
	v_add_f32_dpp v12, v12, v12 row_mirror row_mask:0xf bank_mask:0xf bound_ctrl:1
	ds_read_b128 v[132:135], v84 offset:16896
	ds_read_b128 v[120:123], v84 offset:16128
	ds_read_b128 v[128:131], v84 offset:16640
	ds_read_b128 v[92:95], v96 offset:48
	ds_read_b128 v[124:127], v84 offset:16384
	ds_read_b128 v[136:139], v84 offset:17152
	v_pk_fma_f32 v[2:3], v[172:173], v[12:13], v[6:7] op_sel_hi:[1,0,1] neg_lo:[0,1,0] neg_hi:[0,1,0]
	v_pk_fma_f32 v[4:5], v[174:175], v[12:13], v[8:9] op_sel_hi:[1,0,1] neg_lo:[0,1,0] neg_hi:[0,1,0]
	s_waitcnt lgkmcnt(6)
	v_pk_mul_f32 v[10:11], v[2:3], v[34:35]
	v_pk_fma_f32 v[10:11], v[4:5], v[36:37], v[10:11]
	v_pk_mul_f32 v[14:15], v[2:3], v[184:185]
	v_add_f32_e32 v12, v10, v11
	v_pk_fma_f32 v[14:15], v[4:5], v[186:187], v[14:15]
	v_add_f32_e32 v44, v14, v15
	v_add_f32_dpp v12, v12, v12 quad_perm:[1,0,3,2] row_mask:0xf bank_mask:0xf bound_ctrl:1
	v_add_f32_dpp v102, v102, v102 row_mirror row_mask:0xf bank_mask:0x3 bound_ctrl:1
	v_add_f32_dpp v102, v44, v44 row_mirror row_mask:0xf bank_mask:0xc bound_ctrl:1
	v_add_f32_dpp v12, v12, v12 quad_perm:[2,3,0,1] row_mask:0xf bank_mask:0xf bound_ctrl:1
	v_pk_mul_f32 v[6:7], v[30:31], v[118:119] op_sel:[0,1] op_sel_hi:[1,1]
	v_pk_mul_f32 v[8:9], v[32:33], v[118:119] op_sel:[0,1] op_sel_hi:[1,1]
	v_add_f32_dpp v12, v12, v12 row_half_mirror row_mask:0xf bank_mask:0xf bound_ctrl:1
	v_pk_fma_f32 v[6:7], v[2:3], v[22:23], v[6:7]
	v_pk_fma_f32 v[8:9], v[4:5], v[24:25], v[8:9]
	v_add_f32_dpp v12, v12, v12 row_mirror row_mask:0xf bank_mask:0xf bound_ctrl:1
	ds_read_b128 v[156:159], v84 offset:18240
	ds_read_b128 v[144:147], v84 offset:17472
	ds_read_b128 v[152:155], v84 offset:17984
	ds_read_b128 v[148:151], v84 offset:17728
	ds_read_b128 v[160:163], v84 offset:18496
	v_pk_fma_f32 v[2:3], v[26:27], v[12:13], v[6:7] op_sel_hi:[1,0,1] neg_lo:[0,1,0] neg_hi:[0,1,0]
	v_pk_fma_f32 v[4:5], v[28:29], v[12:13], v[8:9] op_sel_hi:[1,0,1] neg_lo:[0,1,0] neg_hi:[0,1,0]
	s_waitcnt lgkmcnt(5)
; #define LAS __attribute__((address_space(3)))
; __device__ __forceinline__ float row16_sum(float v) { v += dpp_f<0xB1>(v); v += dpp_f<0x4E>(v); v += dpp_f<0x141>(v); v += dpp_f<0x140>(v); return v; }
; __device__ __forceinline__ void rwkv_scan_unit(LAS unsigned char* lds, const float* Wd, const float* V, const bf16_t* RKKB, float* Yraw, int p, int rg, int tid) {
;     ...
;             for (int st = 0; st < SCAN_CH; ++st) {
;                 f32x4 wn = w, bn = b, kn = k, kkn = kk, rn = r; float vn = v;
;                 if (st + 1 < SCAN_CH) { const int o = (st + 1) * SCAN_STEP_B;
;                     wn = *(LAS const f32x4*)(sl + o); bn = *(LAS const f32x4*)(sl + o + 256); kn = *(LAS const f32x4*)(sl + o + 512); kkn = *(LAS const f32x4*)(sl + o + 768); rn = *(LAS const f32x4*)(sl + o + 1024);
;                     vn = *(LAS const float*)(vl + o); }
;                 float sa = (S[0] * kk[0] + S[1] * kk[1]) + (S[2] * kk[2] + S[3] * kk[3]);
;                 const f32x4 kvt = k * v;
;                 sa = -row16_sum(sa);
;                 S = S * w + (b * sa + kvt);
;                 yp[st & 15] = (S[0] * r[0] + S[1] * r[1]) + (S[2] * r[2] + S[3] * r[3]);
;                 if ((st & 15) == 15) yo[(size_t)(st - 15) * 64] = tr16_sum(yp, kq);
;                 w = wn; b = bn; k = kn; kk = kkn; r = rn; v = vn;
	v_pk_mul_f32 v[10:11], v[2:3], v[132:133]
	v_pk_fma_f32 v[10:11], v[4:5], v[134:135], v[10:11]
	v_pk_mul_f32 v[14:15], v[2:3], v[38:39]
	v_add_f32_e32 v12, v10, v11
	v_pk_fma_f32 v[14:15], v[4:5], v[40:41], v[14:15]
	v_add_f32_e32 v44, v14, v15
	v_add_f32_dpp v12, v12, v12 quad_perm:[1,0,3,2] row_mask:0xf bank_mask:0xf bound_ctrl:1
	v_add_f32_dpp v103, v103, v103 row_mirror row_mask:0xf bank_mask:0x3 bound_ctrl:1
	v_add_f32_dpp v103, v44, v44 row_mirror row_mask:0xf bank_mask:0xc bound_ctrl:1
	v_add_f32_dpp v12, v12, v12 quad_perm:[2,3,0,1] row_mask:0xf bank_mask:0xf bound_ctrl:1
	v_pk_mul_f32 v[6:7], v[128:129], v[92:93] op_sel_hi:[1,0]
	v_pk_mul_f32 v[8:9], v[130:131], v[92:93] op_sel_hi:[1,0]
	v_add_f32_dpp v12, v12, v12 row_half_mirror row_mask:0xf bank_mask:0xf bound_ctrl:1
	v_pk_fma_f32 v[6:7], v[2:3], v[120:121], v[6:7]
	v_pk_fma_f32 v[8:9], v[4:5], v[122:123], v[8:9]
	v_add_f32_dpp v12, v12, v12 row_mirror row_mask:0xf bank_mask:0xf bound_ctrl:1
	ds_read_b128 v[180:183], v84 offset:19584
	ds_read_b128 v[168:171], v84 offset:18816
	ds_read_b128 v[176:179], v84 offset:19328
	ds_read_b128 v[172:175], v84 offset:19072
	ds_read_b128 v[184:187], v84 offset:19840
	v_pk_fma_f32 v[2:3], v[124:125], v[12:13], v[6:7] op_sel_hi:[1,0,1] neg_lo:[0,1,0] neg_hi:[0,1,0]
	v_pk_fma_f32 v[4:5], v[126:127], v[12:13], v[8:9] op_sel_hi:[1,0,1] neg_lo:[0,1,0] neg_hi:[0,1,0]
	s_waitcnt lgkmcnt(5)
	v_pk_mul_f32 v[10:11], v[2:3], v[156:157]
	v_pk_fma_f32 v[10:11], v[4:5], v[158:159], v[10:11]
	v_pk_mul_f32 v[14:15], v[2:3], v[136:137]
	v_add_f32_e32 v12, v10, v11
	v_pk_fma_f32 v[14:15], v[4:5], v[138:139], v[14:15]
	v_add_f32_e32 v44, v14, v15
	v_add_f32_dpp v12, v12, v12 quad_perm:[1,0,3,2] row_mask:0xf bank_mask:0xf bound_ctrl:1
	v_add_f32_dpp v104, v104, v104 row_mirror row_mask:0xf bank_mask:0x3 bound_ctrl:1
	v_add_f32_dpp v104, v44, v44 row_mirror row_mask:0xf bank_mask:0xc bound_ctrl:1
	v_add_f32_dpp v12, v12, v12 quad_perm:[2,3,0,1] row_mask:0xf bank_mask:0xf bound_ctrl:1
	v_pk_mul_f32 v[6:7], v[152:153], v[92:93] op_sel:[0,1] op_sel_hi:[1,1]
	v_pk_mul_f32 v[8:9], v[154:155], v[92:93] op_sel:[0,1] op_sel_hi:[1,1]
	v_add_f32_dpp v12, v12, v12 row_half_mirror row_mask:0xf bank_mask:0xf bound_ctrl:1
	v_pk_fma_f32 v[6:7], v[2:3], v[144:145], v[6:7]
	v_pk_fma_f32 v[8:9], v[4:5], v[146:147], v[8:9]
	v_add_f32_dpp v12, v12, v12 row_mirror row_mask:0xf bank_mask:0xf bound_ctrl:1
	ds_read_b128 v[34:37], v84 offset:20928
	ds_read_b128 v[22:25], v84 offset:20160
	ds_read_b128 v[30:33], v84 offset:20672
	ds_read_b128 v[26:29], v84 offset:20416
	ds_read_b128 v[38:41], v84 offset:21184
	v_pk_fma_f32 v[2:3], v[148:149], v[12:13], v[6:7] op_sel_hi:[1,0,1] neg_lo:[0,1,0] neg_hi:[0,1,0]
	v_pk_fma_f32 v[4:5], v[150:151], v[12:13], v[8:9] op_sel_hi:[1,0,1] neg_lo:[0,1,0] neg_hi:[0,1,0]
	s_waitcnt lgkmcnt(5)
	v_pk_mul_f32 v[10:11], v[2:3], v[180:181]
	v_pk_fma_f32 v[10:11], v[4:5], v[182:183], v[10:11]
	v_pk_mul_f32 v[14:15], v[2:3], v[160:161]
	v_add_f32_e32 v12, v10, v11
	v_pk_fma_f32 v[14:15], v[4:5], v[162:163], v[14:15]
	v_add_f32_e32 v44, v14, v15
	v_add_f32_dpp v12, v12, v12 quad_perm:[1,0,3,2] row_mask:0xf bank_mask:0xf bound_ctrl:1
	v_add_f32_dpp v105, v105, v105 row_mirror row_mask:0xf bank_mask:0x3 bound_ctrl:1
	v_add_f32_dpp v105, v44, v44 row_mirror row_mask:0xf bank_mask:0xc bound_ctrl:1
	v_add_f32_dpp v12, v12, v12 quad_perm:[2,3,0,1] row_mask:0xf bank_mask:0xf bound_ctrl:1
	v_pk_mul_f32 v[6:7], v[176:177], v[94:95] op_sel_hi:[1,0]
	v_pk_mul_f32 v[8:9], v[178:179], v[94:95] op_sel_hi:[1,0]
	v_add_f32_dpp v12, v12, v12 row_half_mirror row_mask:0xf bank_mask:0xf bound_ctrl:1
	v_pk_fma_f32 v[6:7], v[2:3], v[168:169], v[6:7]
	v_pk_fma_f32 v[8:9], v[4:5], v[170:171], v[8:9]
	v_add_f32_dpp v12, v12, v12 row_mirror row_mask:0xf bank_mask:0xf bound_ctrl:1
	ds_read_b128 v[132:135], v84 offset:22272
	ds_read_b128 v[120:123], v84 offset:21504
	ds_read_b128 v[128:131], v84 offset:22016
	ds_read_b128 v[116:119], v96 offset:64
	ds_read_b128 v[124:127], v84 offset:21760
	ds_read_b128 v[136:139], v84 offset:22528
	v_pk_fma_f32 v[2:3], v[172:173], v[12:13], v[6:7] op_sel_hi:[1,0,1] neg_lo:[0,1,0] neg_hi:[0,1,0]
	v_pk_fma_f32 v[4:5], v[174:175], v[12:13], v[8:9] op_sel_hi:[1,0,1] neg_lo:[0,1,0] neg_hi:[0,1,0]
	s_waitcnt lgkmcnt(6)
	v_pk_mul_f32 v[10:11], v[2:3], v[34:35]
	v_pk_fma_f32 v[10:11], v[4:5], v[36:37], v[10:11]
	v_pk_mul_f32 v[14:15], v[2:3], v[184:185]
	v_add_f32_e32 v12, v10, v11
	v_pk_fma_f32 v[14:15], v[4:5], v[186:187], v[14:15]
	v_add_f32_e32 v44, v14, v15
	v_add_f32_dpp v12, v12, v12 quad_perm:[1,0,3,2] row_mask:0xf bank_mask:0xf bound_ctrl:1
	v_add_f32_dpp v106, v106, v106 row_mirror row_mask:0xf bank_mask:0x3 bound_ctrl:1
	v_add_f32_dpp v106, v44, v44 row_mirror row_mask:0xf bank_mask:0xc bound_ctrl:1
	v_add_f32_dpp v12, v12, v12 quad_perm:[2,3,0,1] row_mask:0xf bank_mask:0xf bound_ctrl:1
	v_pk_mul_f32 v[6:7], v[30:31], v[94:95] op_sel:[0,1] op_sel_hi:[1,1]
	v_pk_mul_f32 v[8:9], v[32:33], v[94:95] op_sel:[0,1] op_sel_hi:[1,1]
	v_add_f32_dpp v12, v12, v12 row_half_mirror row_mask:0xf bank_mask:0xf bound_ctrl:1
	v_pk_fma_f32 v[6:7], v[2:3], v[22:23], v[6:7]
	v_pk_fma_f32 v[8:9], v[4:5], v[24:25], v[8:9]
	v_add_f32_dpp v12, v12, v12 row_mirror row_mask:0xf bank_mask:0xf bound_ctrl:1
	ds_read_b128 v[156:159], v84 offset:23616
	ds_read_b128 v[144:147], v84 offset:22848
	ds_read_b128 v[152:155], v84 offset:23360
	ds_read_b128 v[148:151], v84 offset:23104
	ds_read_b128 v[160:163], v84 offset:23872
	v_pk_fma_f32 v[2:3], v[26:27], v[12:13], v[6:7] op_sel_hi:[1,0,1] neg_lo:[0,1,0] neg_hi:[0,1,0]
	v_pk_fma_f32 v[4:5], v[28:29], v[12:13], v[8:9] op_sel_hi:[1,0,1] neg_lo:[0,1,0] neg_hi:[0,1,0]
	s_waitcnt lgkmcnt(5)
; #define LAS __attribute__((address_space(3)))
; template <int CTRL> __device__ __forceinline__ float dpp_f(float v) { return __int_as_float(__builtin_amdgcn_update_dpp(0, __float_as_int(v), CTRL, 0xf, 0xf, true)); }
; __device__ __forceinline__ float row16_sum(float v) { v += dpp_f<0xB1>(v); v += dpp_f<0x4E>(v); v += dpp_f<0x141>(v); v += dpp_f<0x140>(v); return v; }
; __device__ __forceinline__ float tr16_sum(const float (&p)[16], int kq) {
;     const bool b3 = (kq & 8) != 0, b2 = (kq & 4) != 0, b1 = (kq & 2) != 0, b0 = (kq & 1) != 0;
;     float q[8], r[4], u[2];
; #pragma unroll
;     for (int t = 0; t < 8; ++t) { const float keep = b3 ? p[t + 8] : p[t], send = b3 ? p[t] : p[t + 8]; q[t] = keep + dpp_f<0x140>(send); }
; #pragma unroll
;     for (int t = 0; t < 4; ++t) { const float keep = b2 ? q[t + 4] : q[t], send = b2 ? q[t] : q[t + 4]; r[t] = keep + dpp_f<0x141>(send); }
; #pragma unroll
;     for (int t = 0; t < 2; ++t) { const float keep = b1 ? r[t + 2] : r[t], send = b1 ? r[t] : r[t + 2]; u[t] = keep + dpp_f<0x4E>(send); }
;     const float keep = b0 ? u[1] : u[0], send = b0 ? u[0] : u[1];
;     return keep + dpp_f<0xB1>(send);
; }
; __device__ __forceinline__ void rwkv_scan_unit(LAS unsigned char* lds, const float* Wd, const float* V, const bf16_t* RKKB, float* Yraw, int p, int rg, int tid) {
;     ...
;             for (int st = 0; st < SCAN_CH; ++st) {
;                 f32x4 wn = w, bn = b, kn = k, kkn = kk, rn = r; float vn = v;
;                 if (st + 1 < SCAN_CH) { const int o = (st + 1) * SCAN_STEP_B;
;                     wn = *(LAS const f32x4*)(sl + o); bn = *(LAS const f32x4*)(sl + o + 256); kn = *(LAS const f32x4*)(sl + o + 512); kkn = *(LAS const f32x4*)(sl + o + 768); rn = *(LAS const f32x4*)(sl + o + 1024);
;                     vn = *(LAS const float*)(vl + o); }
;                 float sa = (S[0] * kk[0] + S[1] * kk[1]) + (S[2] * kk[2] + S[3] * kk[3]);
;                 const f32x4 kvt = k * v;
;                 sa = -row16_sum(sa);
;                 S = S * w + (b * sa + kvt);
;                 yp[st & 15] = (S[0] * r[0] + S[1] * r[1]) + (S[2] * r[2] + S[3] * r[3]);
;                 if ((st & 15) == 15) yo[(size_t)(st - 15) * 64] = tr16_sum(yp, kq);
;                 w = wn; b = bn; k = kn; kk = kkn; r = rn; v = vn;
	v_pk_mul_f32 v[10:11], v[2:3], v[132:133]
	v_pk_fma_f32 v[10:11], v[4:5], v[134:135], v[10:11]
	v_pk_mul_f32 v[14:15], v[2:3], v[38:39]
	v_add_f32_e32 v12, v10, v11
	v_pk_fma_f32 v[14:15], v[4:5], v[40:41], v[14:15]
	v_add_f32_e32 v44, v14, v15
	v_add_f32_dpp v107, v107, v107 row_mirror row_mask:0xf bank_mask:0x3 bound_ctrl:1
	s_nop 0
	v_add_f32_dpp v107, v44, v44 row_mirror row_mask:0xf bank_mask:0xc bound_ctrl:1
	v_add_f32_dpp v12, v12, v12 quad_perm:[1,0,3,2] row_mask:0xf bank_mask:0xf bound_ctrl:1
	v_pk_mul_f32 v[6:7], v[128:129], v[116:117] op_sel_hi:[1,0]
	v_pk_mul_f32 v[8:9], v[130:131], v[116:117] op_sel_hi:[1,0]
	v_pk_fma_f32 v[6:7], v[2:3], v[120:121], v[6:7]
	v_pk_fma_f32 v[8:9], v[4:5], v[122:123], v[8:9]
	v_add_f32_dpp v12, v12, v12 quad_perm:[2,3,0,1] row_mask:0xf bank_mask:0xf bound_ctrl:1
	ds_read_b128 v[180:183], v84 offset:24960
	ds_read_b128 v[168:171], v84 offset:24192
	ds_read_b128 v[176:179], v84 offset:24704
	ds_read_b128 v[172:175], v84 offset:24448
	v_add_f32_dpp v12, v12, v12 row_half_mirror row_mask:0xf bank_mask:0xf bound_ctrl:1
	ds_read_b128 v[184:187], v84 offset:25216
	v_add_f32_dpp v100, v100, v100 row_half_mirror row_mask:0xf bank_mask:0x5 bound_ctrl:1
	v_add_f32_dpp v100, v104, v104 row_half_mirror row_mask:0xf bank_mask:0xa bound_ctrl:1
	v_add_f32_dpp v101, v101, v101 row_half_mirror row_mask:0xf bank_mask:0x5 bound_ctrl:1
	v_add_f32_dpp v12, v12, v12 row_mirror row_mask:0xf bank_mask:0xf bound_ctrl:1
	v_add_f32_dpp v101, v105, v105 row_half_mirror row_mask:0xf bank_mask:0xa bound_ctrl:1
	v_add_f32_dpp v102, v102, v102 row_half_mirror row_mask:0xf bank_mask:0x5 bound_ctrl:1
	v_add_f32_dpp v102, v106, v106 row_half_mirror row_mask:0xf bank_mask:0xa bound_ctrl:1
	v_add_f32_dpp v103, v103, v103 row_half_mirror row_mask:0xf bank_mask:0x5 bound_ctrl:1
	v_add_f32_dpp v103, v107, v107 row_half_mirror row_mask:0xf bank_mask:0xa bound_ctrl:1
	v_cndmask_b32_e64 v16, v102, v100, s[8:9]
	v_pk_fma_f32 v[2:3], v[124:125], v[12:13], v[6:7] op_sel_hi:[1,0,1] neg_lo:[0,1,0] neg_hi:[0,1,0]
	v_pk_fma_f32 v[4:5], v[126:127], v[12:13], v[8:9] op_sel_hi:[1,0,1] neg_lo:[0,1,0] neg_hi:[0,1,0]
	s_waitcnt lgkmcnt(5)
	v_pk_mul_f32 v[10:11], v[2:3], v[156:157]
	v_pk_fma_f32 v[10:11], v[4:5], v[158:159], v[10:11]
	v_pk_mul_f32 v[14:15], v[2:3], v[136:137]
	v_add_f32_e32 v12, v10, v11
	v_pk_fma_f32 v[14:15], v[4:5], v[138:139], v[14:15]
	v_add_f32_e32 v108, v14, v15
	v_pk_mul_f32 v[6:7], v[152:153], v[116:117] op_sel:[0,1] op_sel_hi:[1,1]
	v_pk_mul_f32 v[8:9], v[154:155], v[116:117] op_sel:[0,1] op_sel_hi:[1,1]
	v_add_f32_dpp v12, v12, v12 quad_perm:[1,0,3,2] row_mask:0xf bank_mask:0xf bound_ctrl:1
	v_pk_fma_f32 v[6:7], v[2:3], v[144:145], v[6:7]
	v_pk_fma_f32 v[8:9], v[4:5], v[146:147], v[8:9]
	ds_read_b128 v[34:37], v84 offset:26304
	ds_read_b128 v[22:25], v84 offset:25536
	v_add_f32_dpp v12, v12, v12 quad_perm:[2,3,0,1] row_mask:0xf bank_mask:0xf bound_ctrl:1
	ds_read_b128 v[30:33], v84 offset:26048
	ds_read_b128 v[26:29], v84 offset:25792
	ds_read_b128 v[38:41], v84 offset:26560
	v_cndmask_b32_e64 v17, v100, v102, s[8:9]
	v_add_f32_dpp v12, v12, v12 row_half_mirror row_mask:0xf bank_mask:0xf bound_ctrl:1
	s_nop 0
	v_add_f32_dpp v16, v17, v16 quad_perm:[2,3,0,1] row_mask:0xf bank_mask:0xf bound_ctrl:1
	v_cndmask_b32_e64 v18, v103, v101, s[8:9]
	v_cndmask_b32_e64 v19, v101, v103, s[8:9]
	s_nop 1
	v_add_f32_dpp v18, v19, v18 quad_perm:[2,3,0,1] row_mask:0xf bank_mask:0xf bound_ctrl:1
	v_add_f32_dpp v12, v12, v12 row_mirror row_mask:0xf bank_mask:0xf bound_ctrl:1
	v_cndmask_b32_e64 v17, v18, v16, s[10:11]
	v_cndmask_b32_e64 v19, v16, v18, s[10:11]
	s_nop 1
	v_add_f32_dpp v17, v19, v17 quad_perm:[1,0,3,2] row_mask:0xf bank_mask:0xf bound_ctrl:1
	global_store_dword v[88:89], v17, off
	v_pk_fma_f32 v[2:3], v[148:149], v[12:13], v[6:7] op_sel_hi:[1,0,1] neg_lo:[0,1,0] neg_hi:[0,1,0]
	v_pk_fma_f32 v[4:5], v[150:151], v[12:13], v[8:9] op_sel_hi:[1,0,1] neg_lo:[0,1,0] neg_hi:[0,1,0]
	s_waitcnt lgkmcnt(5)
	v_pk_mul_f32 v[10:11], v[2:3], v[180:181]
	v_pk_fma_f32 v[10:11], v[4:5], v[182:183], v[10:11]
	v_pk_mul_f32 v[14:15], v[2:3], v[160:161]
	v_add_f32_e32 v12, v10, v11
	v_pk_fma_f32 v[14:15], v[4:5], v[162:163], v[14:15]
	v_add_f32_e32 v109, v14, v15
	v_add_f32_dpp v12, v12, v12 quad_perm:[1,0,3,2] row_mask:0xf bank_mask:0xf bound_ctrl:1
	v_pk_mul_f32 v[6:7], v[176:177], v[118:119] op_sel_hi:[1,0]
	v_pk_mul_f32 v[8:9], v[178:179], v[118:119] op_sel_hi:[1,0]
	v_add_f32_dpp v12, v12, v12 quad_perm:[2,3,0,1] row_mask:0xf bank_mask:0xf bound_ctrl:1
	v_pk_fma_f32 v[6:7], v[2:3], v[168:169], v[6:7]
	v_pk_fma_f32 v[8:9], v[4:5], v[170:171], v[8:9]
	v_add_f32_dpp v12, v12, v12 row_half_mirror row_mask:0xf bank_mask:0xf bound_ctrl:1
	ds_read_b128 v[132:135], v84 offset:27648
	ds_read_b128 v[120:123], v84 offset:26880
	v_add_f32_dpp v12, v12, v12 row_mirror row_mask:0xf bank_mask:0xf bound_ctrl:1
	ds_read_b128 v[128:131], v84 offset:27392
	ds_read_b128 v[92:95], v96 offset:80
	ds_read_b128 v[124:127], v84 offset:27136
	ds_read_b128 v[136:139], v84 offset:27904
	v_pk_fma_f32 v[2:3], v[172:173], v[12:13], v[6:7] op_sel_hi:[1,0,1] neg_lo:[0,1,0] neg_hi:[0,1,0]
	v_pk_fma_f32 v[4:5], v[174:175], v[12:13], v[8:9] op_sel_hi:[1,0,1] neg_lo:[0,1,0] neg_hi:[0,1,0]
	s_waitcnt lgkmcnt(6)
; #define LAS __attribute__((address_space(3)))
; __device__ __forceinline__ float row16_sum(float v) { v += dpp_f<0xB1>(v); v += dpp_f<0x4E>(v); v += dpp_f<0x141>(v); v += dpp_f<0x140>(v); return v; }
; __device__ __forceinline__ void rwkv_scan_unit(LAS unsigned char* lds, const float* Wd, const float* V, const bf16_t* RKKB, float* Yraw, int p, int rg, int tid) {
;     ...
;             for (int st = 0; st < SCAN_CH; ++st) {
;                 f32x4 wn = w, bn = b, kn = k, kkn = kk, rn = r; float vn = v;
;                 if (st + 1 < SCAN_CH) { const int o = (st + 1) * SCAN_STEP_B;
;                     wn = *(LAS const f32x4*)(sl + o); bn = *(LAS const f32x4*)(sl + o + 256); kn = *(LAS const f32x4*)(sl + o + 512); kkn = *(LAS const f32x4*)(sl + o + 768); rn = *(LAS const f32x4*)(sl + o + 1024);
;                     vn = *(LAS const float*)(vl + o); }
;                 float sa = (S[0] * kk[0] + S[1] * kk[1]) + (S[2] * kk[2] + S[3] * kk[3]);
;                 const f32x4 kvt = k * v;
;                 sa = -row16_sum(sa);
;                 S = S * w + (b * sa + kvt);
;                 yp[st & 15] = (S[0] * r[0] + S[1] * r[1]) + (S[2] * r[2] + S[3] * r[3]);
;                 if ((st & 15) == 15) yo[(size_t)(st - 15) * 64] = tr16_sum(yp, kq);
;                 w = wn; b = bn; k = kn; kk = kkn; r = rn; v = vn;
	v_pk_mul_f32 v[10:11], v[2:3], v[34:35]
	v_pk_fma_f32 v[10:11], v[4:5], v[36:37], v[10:11]
	v_pk_mul_f32 v[14:15], v[2:3], v[184:185]
	v_add_f32_e32 v12, v10, v11
	v_pk_fma_f32 v[14:15], v[4:5], v[186:187], v[14:15]
	v_add_f32_e32 v110, v14, v15
	v_add_f32_dpp v12, v12, v12 quad_perm:[1,0,3,2] row_mask:0xf bank_mask:0xf bound_ctrl:1
	v_pk_mul_f32 v[6:7], v[30:31], v[118:119] op_sel:[0,1] op_sel_hi:[1,1]
	v_pk_mul_f32 v[8:9], v[32:33], v[118:119] op_sel:[0,1] op_sel_hi:[1,1]
	v_add_f32_dpp v12, v12, v12 quad_perm:[2,3,0,1] row_mask:0xf bank_mask:0xf bound_ctrl:1
	v_pk_fma_f32 v[6:7], v[2:3], v[22:23], v[6:7]
	v_pk_fma_f32 v[8:9], v[4:5], v[24:25], v[8:9]
	v_add_f32_dpp v12, v12, v12 row_half_mirror row_mask:0xf bank_mask:0xf bound_ctrl:1
	ds_read_b128 v[156:159], v84 offset:28992
	ds_read_b128 v[144:147], v84 offset:28224
	v_add_f32_dpp v12, v12, v12 row_mirror row_mask:0xf bank_mask:0xf bound_ctrl:1
	ds_read_b128 v[152:155], v84 offset:28736
	ds_read_b128 v[148:151], v84 offset:28480
	ds_read_b128 v[160:163], v84 offset:29248
	v_pk_fma_f32 v[2:3], v[26:27], v[12:13], v[6:7] op_sel_hi:[1,0,1] neg_lo:[0,1,0] neg_hi:[0,1,0]
	v_pk_fma_f32 v[4:5], v[28:29], v[12:13], v[8:9] op_sel_hi:[1,0,1] neg_lo:[0,1,0] neg_hi:[0,1,0]
	s_waitcnt lgkmcnt(5)
	v_pk_mul_f32 v[10:11], v[2:3], v[132:133]
	v_pk_fma_f32 v[10:11], v[4:5], v[134:135], v[10:11]
	v_pk_mul_f32 v[14:15], v[2:3], v[38:39]
	v_add_f32_e32 v12, v10, v11
	v_pk_fma_f32 v[14:15], v[4:5], v[40:41], v[14:15]
	v_add_f32_e32 v111, v14, v15
	v_add_f32_dpp v12, v12, v12 quad_perm:[1,0,3,2] row_mask:0xf bank_mask:0xf bound_ctrl:1
	v_pk_mul_f32 v[6:7], v[128:129], v[92:93] op_sel_hi:[1,0]
	v_pk_mul_f32 v[8:9], v[130:131], v[92:93] op_sel_hi:[1,0]
	v_add_f32_dpp v12, v12, v12 quad_perm:[2,3,0,1] row_mask:0xf bank_mask:0xf bound_ctrl:1
	v_pk_fma_f32 v[6:7], v[2:3], v[120:121], v[6:7]
	v_pk_fma_f32 v[8:9], v[4:5], v[122:123], v[8:9]
	v_add_f32_dpp v12, v12, v12 row_half_mirror row_mask:0xf bank_mask:0xf bound_ctrl:1
	ds_read_b128 v[180:183], v84 offset:30336
	ds_read_b128 v[168:171], v84 offset:29568
	v_add_f32_dpp v12, v12, v12 row_mirror row_mask:0xf bank_mask:0xf bound_ctrl:1
	ds_read_b128 v[176:179], v84 offset:30080
	ds_read_b128 v[172:175], v84 offset:29824
	ds_read_b128 v[184:187], v84 offset:30592
	v_pk_fma_f32 v[2:3], v[124:125], v[12:13], v[6:7] op_sel_hi:[1,0,1] neg_lo:[0,1,0] neg_hi:[0,1,0]
	v_pk_fma_f32 v[4:5], v[126:127], v[12:13], v[8:9] op_sel_hi:[1,0,1] neg_lo:[0,1,0] neg_hi:[0,1,0]
	s_waitcnt lgkmcnt(5)
	v_pk_mul_f32 v[10:11], v[2:3], v[156:157]
	v_pk_fma_f32 v[10:11], v[4:5], v[158:159], v[10:11]
	v_pk_mul_f32 v[14:15], v[2:3], v[136:137]
	v_add_f32_e32 v12, v10, v11
	v_pk_fma_f32 v[14:15], v[4:5], v[138:139], v[14:15]
	v_add_f32_e32 v112, v14, v15
	v_add_f32_dpp v12, v12, v12 quad_perm:[1,0,3,2] row_mask:0xf bank_mask:0xf bound_ctrl:1
	v_pk_mul_f32 v[6:7], v[152:153], v[92:93] op_sel:[0,1] op_sel_hi:[1,1]
	v_pk_mul_f32 v[8:9], v[154:155], v[92:93] op_sel:[0,1] op_sel_hi:[1,1]
	v_add_f32_dpp v12, v12, v12 quad_perm:[2,3,0,1] row_mask:0xf bank_mask:0xf bound_ctrl:1
	v_pk_fma_f32 v[6:7], v[2:3], v[144:145], v[6:7]
	v_pk_fma_f32 v[8:9], v[4:5], v[146:147], v[8:9]
	v_add_f32_dpp v12, v12, v12 row_half_mirror row_mask:0xf bank_mask:0xf bound_ctrl:1
	ds_read_b128 v[34:37], v84 offset:31680
	ds_read_b128 v[22:25], v84 offset:30912
	v_add_f32_dpp v12, v12, v12 row_mirror row_mask:0xf bank_mask:0xf bound_ctrl:1
	ds_read_b128 v[30:33], v84 offset:31424
	ds_read_b128 v[26:29], v84 offset:31168
	ds_read_b128 v[38:41], v84 offset:31936
	v_pk_fma_f32 v[2:3], v[148:149], v[12:13], v[6:7] op_sel_hi:[1,0,1] neg_lo:[0,1,0] neg_hi:[0,1,0]
	v_pk_fma_f32 v[4:5], v[150:151], v[12:13], v[8:9] op_sel_hi:[1,0,1] neg_lo:[0,1,0] neg_hi:[0,1,0]
	s_waitcnt lgkmcnt(5)
	v_pk_mul_f32 v[10:11], v[2:3], v[180:181]
	v_pk_fma_f32 v[10:11], v[4:5], v[182:183], v[10:11]
	v_pk_mul_f32 v[14:15], v[2:3], v[160:161]
	v_add_f32_e32 v12, v10, v11
	v_pk_fma_f32 v[14:15], v[4:5], v[162:163], v[14:15]
	v_add_f32_e32 v113, v14, v15
	v_add_f32_dpp v12, v12, v12 quad_perm:[1,0,3,2] row_mask:0xf bank_mask:0xf bound_ctrl:1
	v_pk_mul_f32 v[6:7], v[176:177], v[94:95] op_sel_hi:[1,0]
	v_pk_mul_f32 v[8:9], v[178:179], v[94:95] op_sel_hi:[1,0]
	v_add_f32_dpp v12, v12, v12 quad_perm:[2,3,0,1] row_mask:0xf bank_mask:0xf bound_ctrl:1
	v_pk_fma_f32 v[6:7], v[2:3], v[168:169], v[6:7]
	v_pk_fma_f32 v[8:9], v[4:5], v[170:171], v[8:9]
	v_add_f32_dpp v12, v12, v12 row_half_mirror row_mask:0xf bank_mask:0xf bound_ctrl:1
	ds_read_b128 v[132:135], v84 offset:33024
	ds_read_b128 v[120:123], v84 offset:32256
	v_add_f32_dpp v12, v12, v12 row_mirror row_mask:0xf bank_mask:0xf bound_ctrl:1
	ds_read_b128 v[128:131], v84 offset:32768
	ds_read_b128 v[116:119], v96 offset:96
	ds_read_b128 v[124:127], v84 offset:32512
	ds_read_b128 v[136:139], v84 offset:33280
	v_pk_fma_f32 v[2:3], v[172:173], v[12:13], v[6:7] op_sel_hi:[1,0,1] neg_lo:[0,1,0] neg_hi:[0,1,0]
	v_pk_fma_f32 v[4:5], v[174:175], v[12:13], v[8:9] op_sel_hi:[1,0,1] neg_lo:[0,1,0] neg_hi:[0,1,0]
	s_waitcnt lgkmcnt(6)
; #define LAS __attribute__((address_space(3)))
; __device__ __forceinline__ float row16_sum(float v) { v += dpp_f<0xB1>(v); v += dpp_f<0x4E>(v); v += dpp_f<0x141>(v); v += dpp_f<0x140>(v); return v; }
; __device__ __forceinline__ void rwkv_scan_unit(LAS unsigned char* lds, const float* Wd, const float* V, const bf16_t* RKKB, float* Yraw, int p, int rg, int tid) {
;     ...
;             for (int st = 0; st < SCAN_CH; ++st) {
;                 f32x4 wn = w, bn = b, kn = k, kkn = kk, rn = r; float vn = v;
;                 if (st + 1 < SCAN_CH) { const int o = (st + 1) * SCAN_STEP_B;
;                     wn = *(LAS const f32x4*)(sl + o); bn = *(LAS const f32x4*)(sl + o + 256); kn = *(LAS const f32x4*)(sl + o + 512); kkn = *(LAS const f32x4*)(sl + o + 768); rn = *(LAS const f32x4*)(sl + o + 1024);
;                     vn = *(LAS const float*)(vl + o); }
;                 float sa = (S[0] * kk[0] + S[1] * kk[1]) + (S[2] * kk[2] + S[3] * kk[3]);
;                 const f32x4 kvt = k * v;
;                 sa = -row16_sum(sa);
;                 S = S * w + (b * sa + kvt);
;                 yp[st & 15] = (S[0] * r[0] + S[1] * r[1]) + (S[2] * r[2] + S[3] * r[3]);
;                 if ((st & 15) == 15) yo[(size_t)(st - 15) * 64] = tr16_sum(yp, kq);
;                 w = wn; b = bn; k = kn; kk = kkn; r = rn; v = vn;
;             }
	v_pk_mul_f32 v[10:11], v[2:3], v[34:35]
	v_pk_fma_f32 v[10:11], v[4:5], v[36:37], v[10:11]
	v_pk_mul_f32 v[14:15], v[2:3], v[184:185]
	v_add_f32_e32 v12, v10, v11
	v_pk_fma_f32 v[14:15], v[4:5], v[186:187], v[14:15]
	v_add_f32_e32 v114, v14, v15
	v_add_f32_dpp v12, v12, v12 quad_perm:[1,0,3,2] row_mask:0xf bank_mask:0xf bound_ctrl:1
	v_pk_mul_f32 v[6:7], v[30:31], v[94:95] op_sel:[0,1] op_sel_hi:[1,1]
	v_pk_mul_f32 v[8:9], v[32:33], v[94:95] op_sel:[0,1] op_sel_hi:[1,1]
	v_add_f32_dpp v12, v12, v12 quad_perm:[2,3,0,1] row_mask:0xf bank_mask:0xf bound_ctrl:1
	v_pk_fma_f32 v[6:7], v[2:3], v[22:23], v[6:7]
	v_pk_fma_f32 v[8:9], v[4:5], v[24:25], v[8:9]
	v_add_f32_dpp v12, v12, v12 row_half_mirror row_mask:0xf bank_mask:0xf bound_ctrl:1
	ds_read_b128 v[156:159], v84 offset:34368
	ds_read_b128 v[144:147], v84 offset:33600
	v_add_f32_dpp v12, v12, v12 row_mirror row_mask:0xf bank_mask:0xf bound_ctrl:1
	ds_read_b128 v[152:155], v84 offset:34112
	ds_read_b128 v[148:151], v84 offset:33856
	ds_read_b128 v[160:163], v84 offset:34624
	v_pk_fma_f32 v[2:3], v[26:27], v[12:13], v[6:7] op_sel_hi:[1,0,1] neg_lo:[0,1,0] neg_hi:[0,1,0]
	v_pk_fma_f32 v[4:5], v[28:29], v[12:13], v[8:9] op_sel_hi:[1,0,1] neg_lo:[0,1,0] neg_hi:[0,1,0]
	s_waitcnt lgkmcnt(5)
	v_pk_mul_f32 v[10:11], v[2:3], v[132:133]
	v_pk_fma_f32 v[10:11], v[4:5], v[134:135], v[10:11]
	v_pk_mul_f32 v[14:15], v[2:3], v[38:39]
	v_add_f32_e32 v12, v10, v11
	v_pk_fma_f32 v[14:15], v[4:5], v[40:41], v[14:15]
	v_add_f32_e32 v115, v14, v15
	v_add_f32_dpp v12, v12, v12 quad_perm:[1,0,3,2] row_mask:0xf bank_mask:0xf bound_ctrl:1
	v_pk_mul_f32 v[6:7], v[128:129], v[116:117] op_sel_hi:[1,0]
	v_pk_mul_f32 v[8:9], v[130:131], v[116:117] op_sel_hi:[1,0]
	v_add_f32_dpp v12, v12, v12 quad_perm:[2,3,0,1] row_mask:0xf bank_mask:0xf bound_ctrl:1
	v_pk_fma_f32 v[6:7], v[2:3], v[120:121], v[6:7]
	v_pk_fma_f32 v[8:9], v[4:5], v[122:123], v[8:9]
	v_add_f32_dpp v12, v12, v12 row_half_mirror row_mask:0xf bank_mask:0xf bound_ctrl:1
	ds_read_b128 v[180:183], v84 offset:35712
	ds_read_b128 v[168:171], v84 offset:34944
	v_add_f32_dpp v12, v12, v12 row_mirror row_mask:0xf bank_mask:0xf bound_ctrl:1
	ds_read_b128 v[176:179], v84 offset:35456
	ds_read_b128 v[172:175], v84 offset:35200
	ds_read_b128 v[184:187], v84 offset:35968
	v_pk_fma_f32 v[2:3], v[124:125], v[12:13], v[6:7] op_sel_hi:[1,0,1] neg_lo:[0,1,0] neg_hi:[0,1,0]
	v_pk_fma_f32 v[4:5], v[126:127], v[12:13], v[8:9] op_sel_hi:[1,0,1] neg_lo:[0,1,0] neg_hi:[0,1,0]
	s_waitcnt lgkmcnt(5)
	v_pk_mul_f32 v[10:11], v[2:3], v[156:157]
	v_pk_fma_f32 v[10:11], v[4:5], v[158:159], v[10:11]
	v_pk_mul_f32 v[14:15], v[2:3], v[136:137]
	v_add_f32_e32 v12, v10, v11
	v_pk_fma_f32 v[14:15], v[4:5], v[138:139], v[14:15]
	v_add_f32_e32 v44, v14, v15
	v_add_f32_dpp v12, v12, v12 quad_perm:[1,0,3,2] row_mask:0xf bank_mask:0xf bound_ctrl:1
	v_add_f32_dpp v108, v108, v108 row_mirror row_mask:0xf bank_mask:0x3 bound_ctrl:1
	v_add_f32_dpp v108, v44, v44 row_mirror row_mask:0xf bank_mask:0xc bound_ctrl:1
	v_add_f32_dpp v12, v12, v12 quad_perm:[2,3,0,1] row_mask:0xf bank_mask:0xf bound_ctrl:1
	v_pk_mul_f32 v[6:7], v[152:153], v[116:117] op_sel:[0,1] op_sel_hi:[1,1]
	v_pk_mul_f32 v[8:9], v[154:155], v[116:117] op_sel:[0,1] op_sel_hi:[1,1]
	v_add_f32_dpp v12, v12, v12 row_half_mirror row_mask:0xf bank_mask:0xf bound_ctrl:1
	v_pk_fma_f32 v[6:7], v[2:3], v[144:145], v[6:7]
	v_pk_fma_f32 v[8:9], v[4:5], v[146:147], v[8:9]
	v_add_f32_dpp v12, v12, v12 row_mirror row_mask:0xf bank_mask:0xf bound_ctrl:1
	ds_read_b128 v[34:37], v84 offset:37056
	ds_read_b128 v[22:25], v84 offset:36288
	ds_read_b128 v[30:33], v84 offset:36800
	ds_read_b128 v[26:29], v84 offset:36544
	ds_read_b128 v[38:41], v84 offset:37312
	v_pk_fma_f32 v[2:3], v[148:149], v[12:13], v[6:7] op_sel_hi:[1,0,1] neg_lo:[0,1,0] neg_hi:[0,1,0]
	v_pk_fma_f32 v[4:5], v[150:151], v[12:13], v[8:9] op_sel_hi:[1,0,1] neg_lo:[0,1,0] neg_hi:[0,1,0]
	s_waitcnt lgkmcnt(5)
	v_pk_mul_f32 v[10:11], v[2:3], v[180:181]
	v_pk_fma_f32 v[10:11], v[4:5], v[182:183], v[10:11]
	v_pk_mul_f32 v[14:15], v[2:3], v[160:161]
	v_add_f32_e32 v12, v10, v11
	v_pk_fma_f32 v[14:15], v[4:5], v[162:163], v[14:15]
	v_add_f32_e32 v44, v14, v15
	v_add_f32_dpp v12, v12, v12 quad_perm:[1,0,3,2] row_mask:0xf bank_mask:0xf bound_ctrl:1
	v_add_f32_dpp v109, v109, v109 row_mirror row_mask:0xf bank_mask:0x3 bound_ctrl:1
	v_add_f32_dpp v109, v44, v44 row_mirror row_mask:0xf bank_mask:0xc bound_ctrl:1
	v_add_f32_dpp v12, v12, v12 quad_perm:[2,3,0,1] row_mask:0xf bank_mask:0xf bound_ctrl:1
	v_pk_mul_f32 v[6:7], v[176:177], v[118:119] op_sel_hi:[1,0]
	v_pk_mul_f32 v[8:9], v[178:179], v[118:119] op_sel_hi:[1,0]
	v_add_f32_dpp v12, v12, v12 row_half_mirror row_mask:0xf bank_mask:0xf bound_ctrl:1
	v_pk_fma_f32 v[6:7], v[2:3], v[168:169], v[6:7]
	v_pk_fma_f32 v[8:9], v[4:5], v[170:171], v[8:9]
	v_add_f32_dpp v12, v12, v12 row_mirror row_mask:0xf bank_mask:0xf bound_ctrl:1
	ds_read_b128 v[132:135], v84 offset:38400
	ds_read_b128 v[120:123], v84 offset:37632
	ds_read_b128 v[128:131], v84 offset:38144
	ds_read_b128 v[92:95], v96 offset:112
	ds_read_b128 v[124:127], v84 offset:37888
	ds_read_b128 v[136:139], v84 offset:38656
	v_pk_fma_f32 v[2:3], v[172:173], v[12:13], v[6:7] op_sel_hi:[1,0,1] neg_lo:[0,1,0] neg_hi:[0,1,0]
	v_pk_fma_f32 v[4:5], v[174:175], v[12:13], v[8:9] op_sel_hi:[1,0,1] neg_lo:[0,1,0] neg_hi:[0,1,0]
	s_waitcnt lgkmcnt(6)
; #define LAS __attribute__((address_space(3)))
; __device__ __forceinline__ float row16_sum(float v) { v += dpp_f<0xB1>(v); v += dpp_f<0x4E>(v); v += dpp_f<0x141>(v); v += dpp_f<0x140>(v); return v; }
; __device__ __forceinline__ void rwkv_scan_unit(LAS unsigned char* lds, const float* Wd, const float* V, const bf16_t* RKKB, float* Yraw, int p, int rg, int tid) {
;     ...
;             for (int st = 0; st < SCAN_CH; ++st) {
;                 f32x4 wn = w, bn = b, kn = k, kkn = kk, rn = r; float vn = v;
;                 if (st + 1 < SCAN_CH) { const int o = (st + 1) * SCAN_STEP_B;
;                     wn = *(LAS const f32x4*)(sl + o); bn = *(LAS const f32x4*)(sl + o + 256); kn = *(LAS const f32x4*)(sl + o + 512); kkn = *(LAS const f32x4*)(sl + o + 768); rn = *(LAS const f32x4*)(sl + o + 1024);
;                     vn = *(LAS const float*)(vl + o); }
;                 float sa = (S[0] * kk[0] + S[1] * kk[1]) + (S[2] * kk[2] + S[3] * kk[3]);
;                 const f32x4 kvt = k * v;
;                 sa = -row16_sum(sa);
;                 S = S * w + (b * sa + kvt);
;                 yp[st & 15] = (S[0] * r[0] + S[1] * r[1]) + (S[2] * r[2] + S[3] * r[3]);
;                 if ((st & 15) == 15) yo[(size_t)(st - 15) * 64] = tr16_sum(yp, kq);
;                 w = wn; b = bn; k = kn; kk = kkn; r = rn; v = vn;
;             }
	v_pk_mul_f32 v[10:11], v[2:3], v[34:35]
	v_pk_fma_f32 v[10:11], v[4:5], v[36:37], v[10:11]
	v_pk_mul_f32 v[14:15], v[2:3], v[184:185]
	v_add_f32_e32 v12, v10, v11
	v_pk_fma_f32 v[14:15], v[4:5], v[186:187], v[14:15]
	v_add_f32_e32 v44, v14, v15
	v_add_f32_dpp v12, v12, v12 quad_perm:[1,0,3,2] row_mask:0xf bank_mask:0xf bound_ctrl:1
	v_add_f32_dpp v110, v110, v110 row_mirror row_mask:0xf bank_mask:0x3 bound_ctrl:1
	v_add_f32_dpp v110, v44, v44 row_mirror row_mask:0xf bank_mask:0xc bound_ctrl:1
	v_add_f32_dpp v12, v12, v12 quad_perm:[2,3,0,1] row_mask:0xf bank_mask:0xf bound_ctrl:1
	v_pk_mul_f32 v[6:7], v[30:31], v[118:119] op_sel:[0,1] op_sel_hi:[1,1]
	v_pk_mul_f32 v[8:9], v[32:33], v[118:119] op_sel:[0,1] op_sel_hi:[1,1]
	v_add_f32_dpp v12, v12, v12 row_half_mirror row_mask:0xf bank_mask:0xf bound_ctrl:1
	v_pk_fma_f32 v[6:7], v[2:3], v[22:23], v[6:7]
	v_pk_fma_f32 v[8:9], v[4:5], v[24:25], v[8:9]
	v_add_f32_dpp v12, v12, v12 row_mirror row_mask:0xf bank_mask:0xf bound_ctrl:1
	ds_read_b128 v[156:159], v84 offset:39744
	ds_read_b128 v[144:147], v84 offset:38976
	ds_read_b128 v[152:155], v84 offset:39488
	ds_read_b128 v[148:151], v84 offset:39232
	ds_read_b128 v[160:163], v84 offset:40000
	v_pk_fma_f32 v[2:3], v[26:27], v[12:13], v[6:7] op_sel_hi:[1,0,1] neg_lo:[0,1,0] neg_hi:[0,1,0]
	v_pk_fma_f32 v[4:5], v[28:29], v[12:13], v[8:9] op_sel_hi:[1,0,1] neg_lo:[0,1,0] neg_hi:[0,1,0]
	s_waitcnt lgkmcnt(5)
	v_pk_mul_f32 v[10:11], v[2:3], v[132:133]
	v_pk_fma_f32 v[10:11], v[4:5], v[134:135], v[10:11]
	v_pk_mul_f32 v[14:15], v[2:3], v[38:39]
	v_add_f32_e32 v12, v10, v11
	v_pk_fma_f32 v[14:15], v[4:5], v[40:41], v[14:15]
	v_add_f32_e32 v44, v14, v15
	v_add_f32_dpp v12, v12, v12 quad_perm:[1,0,3,2] row_mask:0xf bank_mask:0xf bound_ctrl:1
	v_add_f32_dpp v111, v111, v111 row_mirror row_mask:0xf bank_mask:0x3 bound_ctrl:1
	v_add_f32_dpp v111, v44, v44 row_mirror row_mask:0xf bank_mask:0xc bound_ctrl:1
	v_add_f32_dpp v12, v12, v12 quad_perm:[2,3,0,1] row_mask:0xf bank_mask:0xf bound_ctrl:1
	v_pk_mul_f32 v[6:7], v[128:129], v[92:93] op_sel_hi:[1,0]
	v_pk_mul_f32 v[8:9], v[130:131], v[92:93] op_sel_hi:[1,0]
	v_add_f32_dpp v12, v12, v12 row_half_mirror row_mask:0xf bank_mask:0xf bound_ctrl:1
	v_pk_fma_f32 v[6:7], v[2:3], v[120:121], v[6:7]
	v_pk_fma_f32 v[8:9], v[4:5], v[122:123], v[8:9]
	v_add_f32_dpp v12, v12, v12 row_mirror row_mask:0xf bank_mask:0xf bound_ctrl:1
	ds_read_b128 v[180:183], v84 offset:41088
	ds_read_b128 v[168:171], v84 offset:40320
	ds_read_b128 v[176:179], v84 offset:40832
	ds_read_b128 v[172:175], v84 offset:40576
	ds_read_b128 v[184:187], v84 offset:41344
	v_pk_fma_f32 v[2:3], v[124:125], v[12:13], v[6:7] op_sel_hi:[1,0,1] neg_lo:[0,1,0] neg_hi:[0,1,0]
	v_pk_fma_f32 v[4:5], v[126:127], v[12:13], v[8:9] op_sel_hi:[1,0,1] neg_lo:[0,1,0] neg_hi:[0,1,0]
	s_waitcnt lgkmcnt(5)
	v_pk_mul_f32 v[10:11], v[2:3], v[156:157]
	v_pk_fma_f32 v[10:11], v[4:5], v[158:159], v[10:11]
	v_pk_mul_f32 v[14:15], v[2:3], v[136:137]
	v_add_f32_e32 v12, v10, v11
	v_pk_fma_f32 v[14:15], v[4:5], v[138:139], v[14:15]
	v_add_f32_e32 v44, v14, v15
	v_add_f32_dpp v12, v12, v12 quad_perm:[1,0,3,2] row_mask:0xf bank_mask:0xf bound_ctrl:1
	v_add_f32_dpp v112, v112, v112 row_mirror row_mask:0xf bank_mask:0x3 bound_ctrl:1
	v_add_f32_dpp v112, v44, v44 row_mirror row_mask:0xf bank_mask:0xc bound_ctrl:1
	v_add_f32_dpp v12, v12, v12 quad_perm:[2,3,0,1] row_mask:0xf bank_mask:0xf bound_ctrl:1
	v_pk_mul_f32 v[6:7], v[152:153], v[92:93] op_sel:[0,1] op_sel_hi:[1,1]
	v_pk_mul_f32 v[8:9], v[154:155], v[92:93] op_sel:[0,1] op_sel_hi:[1,1]
	v_add_f32_dpp v12, v12, v12 row_half_mirror row_mask:0xf bank_mask:0xf bound_ctrl:1
	v_pk_fma_f32 v[6:7], v[2:3], v[144:145], v[6:7]
	v_pk_fma_f32 v[8:9], v[4:5], v[146:147], v[8:9]
	v_add_f32_dpp v12, v12, v12 row_mirror row_mask:0xf bank_mask:0xf bound_ctrl:1
	ds_read_b128 v[34:37], v84 offset:42432
	ds_read_b128 v[22:25], v84 offset:41664
	ds_read_b128 v[30:33], v84 offset:42176
	ds_read_b128 v[26:29], v84 offset:41920
	ds_read_b128 v[38:41], v84 offset:42688
	v_pk_fma_f32 v[2:3], v[148:149], v[12:13], v[6:7] op_sel_hi:[1,0,1] neg_lo:[0,1,0] neg_hi:[0,1,0]
	v_pk_fma_f32 v[4:5], v[150:151], v[12:13], v[8:9] op_sel_hi:[1,0,1] neg_lo:[0,1,0] neg_hi:[0,1,0]
	s_waitcnt lgkmcnt(5)
; #define LAS __attribute__((address_space(3)))
; template <int CTRL> __device__ __forceinline__ float dpp_f(float v) { return __int_as_float(__builtin_amdgcn_update_dpp(0, __float_as_int(v), CTRL, 0xf, 0xf, true)); }
; __device__ __forceinline__ float row16_sum(float v) { v += dpp_f<0xB1>(v); v += dpp_f<0x4E>(v); v += dpp_f<0x141>(v); v += dpp_f<0x140>(v); return v; }
; __device__ __forceinline__ float tr16_sum(const float (&p)[16], int kq) {
;     const bool b3 = (kq & 8) != 0, b2 = (kq & 4) != 0, b1 = (kq & 2) != 0, b0 = (kq & 1) != 0;
;     float q[8], r[4], u[2];
; #pragma unroll
;     for (int t = 0; t < 8; ++t) { const float keep = b3 ? p[t + 8] : p[t], send = b3 ? p[t] : p[t + 8]; q[t] = keep + dpp_f<0x140>(send); }
; #pragma unroll
;     for (int t = 0; t < 4; ++t) { const float keep = b2 ? q[t + 4] : q[t], send = b2 ? q[t] : q[t + 4]; r[t] = keep + dpp_f<0x141>(send); }
; #pragma unroll
;     for (int t = 0; t < 2; ++t) { const float keep = b1 ? r[t + 2] : r[t], send = b1 ? r[t] : r[t + 2]; u[t] = keep + dpp_f<0x4E>(send); }
;     const float keep = b0 ? u[1] : u[0], send = b0 ? u[0] : u[1];
;     return keep + dpp_f<0xB1>(send);
; }
; __device__ __forceinline__ void rwkv_scan_unit(LAS unsigned char* lds, const float* Wd, const float* V, const bf16_t* RKKB, float* Yraw, int p, int rg, int tid) {
;     ...
;             for (int st = 0; st < SCAN_CH; ++st) {
;                 f32x4 wn = w, bn = b, kn = k, kkn = kk, rn = r; float vn = v;
;                 if (st + 1 < SCAN_CH) { const int o = (st + 1) * SCAN_STEP_B;
;                     wn = *(LAS const f32x4*)(sl + o); bn = *(LAS const f32x4*)(sl + o + 256); kn = *(LAS const f32x4*)(sl + o + 512); kkn = *(LAS const f32x4*)(sl + o + 768); rn = *(LAS const f32x4*)(sl + o + 1024);
;                     vn = *(LAS const float*)(vl + o); }
;                 float sa = (S[0] * kk[0] + S[1] * kk[1]) + (S[2] * kk[2] + S[3] * kk[3]);
;                 const f32x4 kvt = k * v;
;                 sa = -row16_sum(sa);
;                 S = S * w + (b * sa + kvt);
;                 yp[st & 15] = (S[0] * r[0] + S[1] * r[1]) + (S[2] * r[2] + S[3] * r[3]);
;                 if ((st & 15) == 15) yo[(size_t)(st - 15) * 64] = tr16_sum(yp, kq);
;                 w = wn; b = bn; k = kn; kk = kkn; r = rn; v = vn;
;             }
;         }
;         __syncthreads();
;     }
	v_pk_mul_f32 v[10:11], v[2:3], v[180:181]
	v_pk_fma_f32 v[10:11], v[4:5], v[182:183], v[10:11]
	v_pk_mul_f32 v[14:15], v[2:3], v[160:161]
	v_add_f32_e32 v12, v10, v11
	v_pk_fma_f32 v[14:15], v[4:5], v[162:163], v[14:15]
	v_add_f32_e32 v44, v14, v15
	v_add_f32_dpp v12, v12, v12 quad_perm:[1,0,3,2] row_mask:0xf bank_mask:0xf bound_ctrl:1
	v_add_f32_dpp v113, v113, v113 row_mirror row_mask:0xf bank_mask:0x3 bound_ctrl:1
	v_add_f32_dpp v113, v44, v44 row_mirror row_mask:0xf bank_mask:0xc bound_ctrl:1
	v_add_f32_dpp v12, v12, v12 quad_perm:[2,3,0,1] row_mask:0xf bank_mask:0xf bound_ctrl:1
	v_pk_mul_f32 v[6:7], v[176:177], v[94:95] op_sel_hi:[1,0]
	v_pk_mul_f32 v[8:9], v[178:179], v[94:95] op_sel_hi:[1,0]
	v_add_f32_dpp v12, v12, v12 row_half_mirror row_mask:0xf bank_mask:0xf bound_ctrl:1
	v_pk_fma_f32 v[6:7], v[2:3], v[168:169], v[6:7]
	v_pk_fma_f32 v[8:9], v[4:5], v[170:171], v[8:9]
	v_add_f32_dpp v12, v12, v12 row_mirror row_mask:0xf bank_mask:0xf bound_ctrl:1
	ds_read_b128 v[132:135], v86 offset:768
	ds_read_b128 v[120:123], v86
	ds_read_b128 v[128:131], v86 offset:512
	ds_read_b128 v[116:119], v97
	ds_read_b128 v[124:127], v86 offset:256
	ds_read_b128 v[136:139], v86 offset:1024
	v_pk_fma_f32 v[2:3], v[172:173], v[12:13], v[6:7] op_sel_hi:[1,0,1] neg_lo:[0,1,0] neg_hi:[0,1,0]
	v_pk_fma_f32 v[4:5], v[174:175], v[12:13], v[8:9] op_sel_hi:[1,0,1] neg_lo:[0,1,0] neg_hi:[0,1,0]
	s_waitcnt lgkmcnt(6)
	v_pk_mul_f32 v[10:11], v[2:3], v[34:35]
	v_pk_fma_f32 v[10:11], v[4:5], v[36:37], v[10:11]
	v_pk_mul_f32 v[14:15], v[2:3], v[184:185]
	v_add_f32_e32 v12, v10, v11
	v_pk_fma_f32 v[14:15], v[4:5], v[186:187], v[14:15]
	v_add_f32_e32 v44, v14, v15
	v_add_f32_dpp v12, v12, v12 quad_perm:[1,0,3,2] row_mask:0xf bank_mask:0xf bound_ctrl:1
	v_add_f32_dpp v114, v114, v114 row_mirror row_mask:0xf bank_mask:0x3 bound_ctrl:1
	v_add_f32_dpp v114, v44, v44 row_mirror row_mask:0xf bank_mask:0xc bound_ctrl:1
	v_add_f32_dpp v12, v12, v12 quad_perm:[2,3,0,1] row_mask:0xf bank_mask:0xf bound_ctrl:1
	v_pk_mul_f32 v[6:7], v[30:31], v[94:95] op_sel:[0,1] op_sel_hi:[1,1]
	v_pk_mul_f32 v[8:9], v[32:33], v[94:95] op_sel:[0,1] op_sel_hi:[1,1]
	v_add_f32_dpp v12, v12, v12 row_half_mirror row_mask:0xf bank_mask:0xf bound_ctrl:1
	v_pk_fma_f32 v[6:7], v[2:3], v[22:23], v[6:7]
	v_pk_fma_f32 v[8:9], v[4:5], v[24:25], v[8:9]
	v_add_f32_dpp v12, v12, v12 row_mirror row_mask:0xf bank_mask:0xf bound_ctrl:1
	ds_read_b128 v[156:159], v86 offset:2112
	ds_read_b128 v[144:147], v86 offset:1344
	ds_read_b128 v[152:155], v86 offset:1856
	ds_read_b128 v[148:151], v86 offset:1600
	ds_read_b128 v[160:163], v86 offset:2368
	v_pk_fma_f32 v[2:3], v[26:27], v[12:13], v[6:7] op_sel_hi:[1,0,1] neg_lo:[0,1,0] neg_hi:[0,1,0]
	v_pk_fma_f32 v[4:5], v[28:29], v[12:13], v[8:9] op_sel_hi:[1,0,1] neg_lo:[0,1,0] neg_hi:[0,1,0]
	v_pk_mul_f32 v[14:15], v[2:3], v[38:39]
	v_pk_fma_f32 v[14:15], v[4:5], v[40:41], v[14:15]
	v_add_f32_e32 v44, v14, v15
	v_add_f32_dpp v115, v115, v115 row_mirror row_mask:0xf bank_mask:0x3 bound_ctrl:1
	s_nop 0
	v_add_f32_dpp v115, v44, v44 row_mirror row_mask:0xf bank_mask:0xc bound_ctrl:1
	v_add_f32_dpp v108, v108, v108 row_half_mirror row_mask:0xf bank_mask:0x5 bound_ctrl:1
	v_add_f32_dpp v108, v112, v112 row_half_mirror row_mask:0xf bank_mask:0xa bound_ctrl:1
	v_add_f32_dpp v109, v109, v109 row_half_mirror row_mask:0xf bank_mask:0x5 bound_ctrl:1
	v_add_f32_dpp v109, v113, v113 row_half_mirror row_mask:0xf bank_mask:0xa bound_ctrl:1
	v_add_f32_dpp v110, v110, v110 row_half_mirror row_mask:0xf bank_mask:0x5 bound_ctrl:1
	v_add_f32_dpp v110, v114, v114 row_half_mirror row_mask:0xf bank_mask:0xa bound_ctrl:1
	v_add_f32_dpp v111, v111, v111 row_half_mirror row_mask:0xf bank_mask:0x5 bound_ctrl:1
	v_add_f32_dpp v111, v115, v115 row_half_mirror row_mask:0xf bank_mask:0xa bound_ctrl:1
	v_cndmask_b32_e64 v16, v110, v108, s[8:9]
	v_cndmask_b32_e64 v17, v108, v110, s[8:9]
	s_nop 1
	v_add_f32_dpp v16, v17, v16 quad_perm:[2,3,0,1] row_mask:0xf bank_mask:0xf bound_ctrl:1
	v_cndmask_b32_e64 v18, v111, v109, s[8:9]
	v_cndmask_b32_e64 v19, v109, v111, s[8:9]
	s_nop 1
	v_add_f32_dpp v18, v19, v18 quad_perm:[2,3,0,1] row_mask:0xf bank_mask:0xf bound_ctrl:1
	v_cndmask_b32_e64 v17, v18, v16, s[10:11]
	v_cndmask_b32_e64 v19, v16, v18, s[10:11]
	s_nop 1
	v_add_f32_dpp v17, v19, v17 quad_perm:[1,0,3,2] row_mask:0xf bank_mask:0xf bound_ctrl:1
	global_store_dword v[90:91], v17, off
	s_add_i32 s22, s22, 1
	s_mov_b64 s[18:19], 0x2000
	v_lshl_add_u64 v[60:61], v[60:61], 0, s[18:19]
	s_mov_b64 s[68:69], 0x2000
	s_cmpk_eq_i32 s22, 0x80
	s_barrier
	s_cbranch_scc1 .LBB0_370
	s_branch .Lscan_top

; #define LAS __attribute__((address_space(3)))
; __device__ __forceinline__ float bflo(unsigned w) { return __uint_as_float(w << 16); }
; __device__ __forceinline__ float bfhi(unsigned w) { return __uint_as_float(w & 0xffff0000u); }
; __device__ __forceinline__ void scan_load_chunk(LAS unsigned char* slot, const float* Wd, const float* V, const bf16_t* RKKB, int p, int rg, int s0, int lt) {
;     ...
;     if (lt < 128) { const int st = lt >> 2, hf = lt & 3; r[6] = *(const u32x4*)(V + (base + st) * 64 + rg * 16 + hf * 4); }
; #pragma unroll
;     for (int j = 0; j < 2; ++j) { const int idx = lt + 256 * j, st = idx >> 4, part = idx & 15; *(LAS u32x4*)(slot + st * SCAN_STEP_B + part * 16) = r[j]; }
; #pragma unroll
;     for (int j = 2; j < 6; ++j) { const int k = lt + 256 * (j - 2), st = k >> 5, rem = k & 31, q = rem >> 3, part = rem & 7; const u32x4 w = r[j];
;         const int Q = (q == 0) ? 4 : (q == 1) ? 2 : (q == 2) ? 3 : 1;
;         LAS f32x4* d = (LAS f32x4*)(slot + st * SCAN_STEP_B + Q * 256 + part * 32);
;         d[0] = (f32x4){bflo(w.x), bfhi(w.x), bflo(w.y), bfhi(w.y)}; d[1] = (f32x4){bflo(w.z), bfhi(w.z), bflo(w.w), bfhi(w.w)}; }
;     if (lt < 128) { const int st = lt >> 2, hf = lt & 3; *(LAS u32x4*)(slot + st * SCAN_STEP_B + 1280 + hf * 16) = r[6]; }
.LBB0_368:
	s_or_b64 exec, exec, s[18:19]
	v_add_u32_e32 v14, s23, v80
	v_add3_u32 v0, v14, v0, v76
	s_waitcnt vmcnt(0)
	v_lshlrev_b32_e32 v14, 16, v6
	v_and_b32_e32 v15, 0xffff0000, v6
	v_lshlrev_b32_e32 v16, 16, v7
	v_and_b32_e32 v17, 0xffff0000, v7
	v_lshlrev_b32_e32 v6, 16, v8
	v_and_b32_e32 v7, 0xffff0000, v8
	v_lshlrev_b32_e32 v8, 16, v9
	v_and_b32_e32 v9, 0xffff0000, v9
	ds_write_b128 v0, v[14:17]
	ds_write_b128 v0, v[6:9] offset:16
	s_and_saveexec_b64 s[18:19], s[12:13]
	s_cbranch_execz .LBB0_343
	s_lshr_b32 s20, s23, 15
	s_lshl_b32 s20, s20, 11
	s_add_i32 s20, s20, 0x1f800
	v_and_b32_e32 v14, 0xfc, v232
	v_and_b32_e32 v0, 3, v232
	v_lshl_or_b32 v0, v0, 9, v14
	v_add_u32_e32 v0, s20, v0
	ds_write_b32 v0, v10
	ds_write_b32 v0, v11 offset:128
	ds_write_b32 v0, v12 offset:256
	ds_write_b32 v0, v13 offset:384
	s_branch .LBB0_343
